# v71 plus memory-attention query rows software-pipelined one 128-row pass ahead (spare registers, copied at the top of the next pass); fixes the scalar-register clash of v72 that made half the workgrou
# speedup vs baseline: 1.0177x; 1.0177x over previous
; __device__ __forceinline__ void unpack8(const v4u w, float (&o)[8]) { o[0] = bflo(w.x); o[1] = bfhi(w.x); o[2] = bflo(w.y); o[3] = bfhi(w.y); o[4] = bflo(w.z); o[5] = bfhi(w.z); o[6] = bflo(w.w); o[7] = bfhi(w.w); }
; template <bool SAMPLE>
; __device__ __forceinline__ void mem_unit(const Params& p, int l, LAS unsigned char* lds, int unit, int tid, int wave, int lane) {
;     ...
;         int q16 = lane & 15, kq = lane >> 4; asm volatile("" : "+v"(q16), "+v"(kq));
;         size_t row; bool st;
;         if (!SAMPLE) { row = (size_t)b * 8192 + (qt * 4 + qq) * 128 + 16 * wave + q16; st = true; } else { row = (size_t)MP + 8 * b + (q16 & 7); st = q16 < 8; }
;         bf16x8 qf[4];
;         {
;             float qv[4][8]; float ss = 0.f;
; #pragma unroll
;             for (int dc = 0; dc < 4; ++dc) { unpack8(*(const v4u*)(MQ + row * 512 + h * 128 + 32 * dc + 8 * kq), qv[dc]);
; #pragma unroll
;                 for (int e = 0; e < 8; ++e) ss += qv[dc][e] * qv[dc][e]; }
;             ss += __shfl_xor(ss, 16); ss += __shfl_xor(ss, 32);
;             const float rs = rsqrtf(ss * (1.f / 128.f) + EPS) * 0.08838834764831845f;
; #pragma unroll
;             for (int dc = 0; dc < 4; ++dc) { float qg[8]; pg8::ld8f(p.in[I_MQG] + l * 128 + 32 * dc + 8 * kq, qg);
.LBB0_631:
	v_mov_b32_e32 v90, v94
	v_mov_b32_e32 v92, v95
	s_add_u32 s16, s10, s8
	s_addc_u32 s17, s18, s9
	v_ashrrev_i32_e32 v91, 31, v90
	v_lshl_add_u64 v[0:1], s[16:17], 0, v[90:91]
	v_lshlrev_b32_e32 v8, 3, v92
	v_lshlrev_b64 v[88:89], 10, v[0:1]
	v_ashrrev_i32_e32 v9, 31, v8
	v_lshl_add_u64 v[10:11], s[0:1], 0, v[88:89]
	v_lshlrev_b32_e32 v2, 4, v92
	v_mul_lo_u32 v3, v90, s30
	v_lshl_add_u64 v[24:25], v[8:9], 2, s[46:47]
	v_lshl_add_u64 v[20:21], v[8:9], 1, v[10:11]
	v_add3_u32 v91, 0, v2, v3
	global_load_dwordx4 v[0:3], v[24:25], off offset:16
	global_load_dwordx4 v[4:7], v[24:25], off
	s_cmp_lg_u32 s8, 0
	s_cbranch_scc1 .Lqpf_have_0
	global_load_dwordx4 v[234:237], v[20:21], off
	global_load_dwordx4 v[242:245], v[20:21], off offset:64
	global_load_dwordx4 v[246:249], v[20:21], off offset:128
	global_load_dwordx4 v[250:253], v[20:21], off offset:192
	s_waitcnt vmcnt(0)
	s_branch .Lqpf_go_0

; __device__ __forceinline__ void unpack8(const v4u w, float (&o)[8]) { o[0] = bflo(w.x); o[1] = bfhi(w.x); o[2] = bflo(w.y); o[3] = bfhi(w.y); o[4] = bflo(w.z); o[5] = bfhi(w.z); o[6] = bflo(w.w); o[7] = bfhi(w.w); }
; __device__ __forceinline__ bf16x8 pack8(const float (&o)[8]) { v4u w; w.x = pk2(o[0], o[1]); w.y = pk2(o[2], o[3]); w.z = pk2(o[4], o[5]); w.w = pk2(o[6], o[7]); return __builtin_bit_cast(bf16x8, w); }
; template <bool SAMPLE>
; __device__ __forceinline__ void mem_unit(const Params& p, int l, LAS unsigned char* lds, int unit, int tid, int wave, int lane) {
;     ...
;         bf16x8 qf[4];
;         {
;             float qv[4][8]; float ss = 0.f;
; #pragma unroll
;             for (int dc = 0; dc < 4; ++dc) { unpack8(*(const v4u*)(MQ + row * 512 + h * 128 + 32 * dc + 8 * kq), qv[dc]);
; #pragma unroll
;                 for (int e = 0; e < 8; ++e) ss += qv[dc][e] * qv[dc][e]; }
;             ss += __shfl_xor(ss, 16); ss += __shfl_xor(ss, 32);
;             const float rs = rsqrtf(ss * (1.f / 128.f) + EPS) * 0.08838834764831845f;
; #pragma unroll
;             for (int dc = 0; dc < 4; ++dc) { float qg[8]; pg8::ld8f(p.in[I_MQG] + l * 128 + 32 * dc + 8 * kq, qg);
; #pragma unroll
;                 for (int e = 0; e < 8; ++e) qv[dc][e] *= rs * qg[e];
;                 qf[dc] = pack8(qv[dc]); }
.Lqpf_go_0:
	s_mov_b32 s100, 0x20000
	s_mov_b32 s101, 0
	v_lshl_add_u64 v[230:231], v[20:21], 0, s[100:101]
	v_mov_b32_e32 v8, v234
	v_mov_b32_e32 v9, v235
	v_mov_b32_e32 v10, v236
	v_mov_b32_e32 v11, v237
	v_mov_b32_e32 v12, v242
	v_mov_b32_e32 v13, v243
	v_mov_b32_e32 v14, v244
	v_mov_b32_e32 v15, v245
	v_mov_b32_e32 v16, v246
	v_mov_b32_e32 v17, v247
	v_mov_b32_e32 v18, v248
	v_mov_b32_e32 v19, v249
	v_mov_b32_e32 v20, v250
	v_mov_b32_e32 v21, v251
	v_mov_b32_e32 v22, v252
	v_mov_b32_e32 v23, v253
	v_lshlrev_b32_e32 v92, 2, v92
	v_ashrrev_i32_e32 v93, 31, v92
	s_add_u32 s8, s8, 0x80
	s_addc_u32 s9, s9, 0
	s_cmpk_lg_i32 s8, 0x200
	s_waitcnt vmcnt(0)
	v_and_b32_e32 v31, 0xffff0000, v8
	v_lshlrev_b32_e32 v30, 16, v8
	v_mul_f32_e32 v50, v31, v31
	v_lshlrev_b32_e32 v32, 16, v9
	v_fmac_f32_e32 v50, v30, v30
	v_and_b32_e32 v33, 0xffff0000, v9
	v_fmac_f32_e32 v50, v32, v32
	v_lshlrev_b32_e32 v34, 16, v10
	v_fmac_f32_e32 v50, v33, v33
	v_and_b32_e32 v35, 0xffff0000, v10
	v_fmac_f32_e32 v50, v34, v34
	v_lshlrev_b32_e32 v36, 16, v11
	v_fmac_f32_e32 v50, v35, v35
	v_and_b32_e32 v37, 0xffff0000, v11
	v_fmac_f32_e32 v50, v36, v36
	s_waitcnt vmcnt(2)
	v_lshlrev_b32_e32 v38, 16, v12
	v_fmac_f32_e32 v50, v37, v37
	v_and_b32_e32 v39, 0xffff0000, v12
	v_fmac_f32_e32 v50, v38, v38
	v_lshlrev_b32_e32 v40, 16, v13
	v_fmac_f32_e32 v50, v39, v39
	v_and_b32_e32 v41, 0xffff0000, v13
	v_fmac_f32_e32 v50, v40, v40
	v_lshlrev_b32_e32 v42, 16, v14
	v_fmac_f32_e32 v50, v41, v41
	v_and_b32_e32 v43, 0xffff0000, v14
	v_fmac_f32_e32 v50, v42, v42
	v_lshlrev_b32_e32 v44, 16, v15
	v_fmac_f32_e32 v50, v43, v43
	v_and_b32_e32 v45, 0xffff0000, v15
	v_fmac_f32_e32 v50, v44, v44
	s_waitcnt vmcnt(1)
	v_lshlrev_b32_e32 v46, 16, v16
	v_fmac_f32_e32 v50, v45, v45
	v_and_b32_e32 v16, 0xffff0000, v16
	v_fmac_f32_e32 v50, v46, v46
	v_lshlrev_b32_e32 v47, 16, v17
	v_fmac_f32_e32 v50, v16, v16
	v_and_b32_e32 v17, 0xffff0000, v17
	v_fmac_f32_e32 v50, v47, v47
	v_lshlrev_b32_e32 v48, 16, v18
	v_fmac_f32_e32 v50, v17, v17
	v_and_b32_e32 v18, 0xffff0000, v18
	v_fmac_f32_e32 v50, v48, v48
	v_lshlrev_b32_e32 v49, 16, v19
	v_fmac_f32_e32 v50, v18, v18
	v_and_b32_e32 v19, 0xffff0000, v19
	s_waitcnt vmcnt(0)
	v_and_b32_e32 v26, 0xffff0000, v20
	v_lshlrev_b32_e32 v27, 16, v20
	v_fmac_f32_e32 v50, v49, v49
	v_pk_mul_f32 v[8:9], v[26:27], v[26:27]
	v_fmac_f32_e32 v50, v19, v19
	v_and_b32_e32 v20, 0xffff0000, v21
	v_lshlrev_b32_e32 v21, 16, v21
	v_add_f32_e32 v9, v9, v50
	v_pk_mul_f32 v[10:11], v[20:21], v[20:21]
	v_add_f32_e32 v8, v8, v9
	v_and_b32_e32 v28, 0xffff0000, v22
	v_lshlrev_b32_e32 v29, 16, v22
	v_add_f32_e32 v8, v11, v8
	v_pk_mul_f32 v[12:13], v[28:29], v[28:29]
	v_add_f32_e32 v8, v10, v8
	v_and_b32_e32 v22, 0xffff0000, v23
	v_lshlrev_b32_e32 v23, 16, v23
	v_add_f32_e32 v8, v13, v8
	v_pk_mul_f32 v[14:15], v[22:23], v[22:23]
	v_add_f32_e32 v8, v12, v8
	v_add_f32_e32 v8, v15, v8
	v_add_f32_e32 v8, v14, v8
	ds_bpermute_b32 v9, v82, v8
	s_waitcnt lgkmcnt(0)
	v_add_f32_e32 v8, v8, v9
	ds_bpermute_b32 v9, v100, v8
	s_waitcnt lgkmcnt(0)
	v_add_f32_e32 v8, v8, v9
	v_fmamk_f32 v8, v8, 0x3c000000, v98
	v_mul_f32_e32 v9, 0x4b800000, v8
	v_cmp_gt_f32_e32 vcc, s31, v8
	s_nop 1
	v_cndmask_b32_e32 v8, v8, v9, vcc
	v_rsq_f32_e32 v8, v8
	s_nop 0
	v_mul_f32_e32 v9, 0x45800000, v8
	v_cndmask_b32_e32 v8, v8, v9, vcc
	v_mul_f32_e32 v50, 0x3db504f3, v8
	v_mul_f32_e32 v4, v4, v50
	v_mul_f32_e32 v5, v5, v50
	v_mul_f32_e32 v6, v6, v50
	v_mul_f32_e32 v7, v7, v50
	v_mul_f32_e32 v0, v0, v50
	v_mul_f32_e32 v1, v1, v50
	v_mul_f32_e32 v2, v2, v50
	v_mul_f32_e32 v3, v3, v50
	v_mul_f32_e32 v4, v4, v30
	v_mul_f32_e32 v5, v5, v31
	v_mul_f32_e32 v6, v6, v32
	v_mul_f32_e32 v7, v7, v33
	v_mul_f32_e32 v0, v0, v34
	v_mul_f32_e32 v1, v1, v35
	v_mul_f32_e32 v2, v2, v36
	v_mul_f32_e32 v3, v3, v37
	v_cvt_pk_bf16_f32 v8, v4, v5
	v_cvt_pk_bf16_f32 v9, v6, v7
	v_cvt_pk_bf16_f32 v10, v0, v1
	v_cvt_pk_bf16_f32 v11, v2, v3
	global_load_dwordx4 v[0:3], v[24:25], off offset:128
	global_load_dwordx4 v[4:7], v[24:25], off offset:144
	s_waitcnt vmcnt(1)
	v_mul_f32_e32 v0, v0, v50
	v_mul_f32_e32 v1, v1, v50
	v_mul_f32_e32 v2, v2, v50
	v_mul_f32_e32 v3, v3, v50
	s_waitcnt vmcnt(0)
	v_mul_f32_e32 v4, v4, v50
	v_mul_f32_e32 v5, v5, v50
	v_mul_f32_e32 v6, v6, v50
	v_mul_f32_e32 v7, v7, v50
	v_mul_f32_e32 v0, v0, v38
	v_mul_f32_e32 v1, v1, v39
	v_mul_f32_e32 v2, v2, v40
	v_mul_f32_e32 v3, v3, v41
	v_mul_f32_e32 v4, v4, v42
	v_mul_f32_e32 v5, v5, v43
	v_mul_f32_e32 v6, v6, v44
	v_mul_f32_e32 v7, v7, v45
	v_cvt_pk_bf16_f32 v12, v0, v1
	v_cvt_pk_bf16_f32 v13, v2, v3
	v_cvt_pk_bf16_f32 v14, v4, v5
	v_cvt_pk_bf16_f32 v15, v6, v7
	global_load_dwordx4 v[0:3], v[24:25], off offset:256
	global_load_dwordx4 v[4:7], v[24:25], off offset:272
	s_waitcnt vmcnt(1)
	v_mul_f32_e32 v0, v0, v50
	v_mul_f32_e32 v1, v1, v50
	v_mul_f32_e32 v2, v2, v50
	v_mul_f32_e32 v3, v3, v50
	s_waitcnt vmcnt(0)
	v_mul_f32_e32 v4, v4, v50
	v_mul_f32_e32 v5, v5, v50
	v_mul_f32_e32 v6, v6, v50
	v_mul_f32_e32 v7, v7, v50
	v_mul_f32_e32 v0, v0, v46
	v_mul_f32_e32 v1, v1, v16
	v_mul_f32_e32 v2, v2, v47
	v_mul_f32_e32 v3, v3, v17
	v_mul_f32_e32 v16, v4, v48
	v_mul_f32_e32 v17, v5, v18
	v_mul_f32_e32 v18, v6, v49
	v_mul_f32_e32 v7, v7, v19
	v_cvt_pk_bf16_f32 v4, v0, v1
	v_cvt_pk_bf16_f32 v5, v2, v3
	v_cvt_pk_bf16_f32 v6, v16, v17
	v_cvt_pk_bf16_f32 v7, v18, v7
	global_load_dwordx4 v[0:3], v[24:25], off offset:384
	global_load_dwordx4 v[16:19], v[24:25], off offset:400
	s_waitcnt vmcnt(1)
	v_mul_f32_e32 v0, v0, v50
	v_mul_f32_e32 v1, v1, v50
	v_mul_f32_e32 v2, v2, v50
	v_mul_f32_e32 v3, v3, v50
	s_waitcnt vmcnt(0)
; #define LAS __attribute__((address_space(3)))
; __device__ __forceinline__ bf16x8 pack8(const float (&o)[8]) { v4u w; w.x = pk2(o[0], o[1]); w.y = pk2(o[2], o[3]); w.z = pk2(o[4], o[5]); w.w = pk2(o[6], o[7]); return __builtin_bit_cast(bf16x8, w); }
; template <bool SAMPLE>
; __device__ __forceinline__ void mem_unit(const Params& p, int l, LAS unsigned char* lds, int unit, int tid, int wave, int lane) {
;     ...
;             for (int dc = 0; dc < 4; ++dc) { float qg[8]; pg8::ld8f(p.in[I_MQG] + l * 128 + 32 * dc + 8 * kq, qg);
; #pragma unroll
;                 for (int e = 0; e < 8; ++e) qv[dc][e] *= rs * qg[e];
;                 qf[dc] = pack8(qv[dc]); }
;         }
;         f32x4 S[8][2]; float mx = -INFINITY;
; #pragma unroll
;         for (int cc = 0; cc < 8; ++cc)
; #pragma unroll
;             for (int tt = 0; tt < 2; ++tt) { const int kb = 32 * cc + 16 * tt; f32x4 a = (f32x4){0.f, 0.f, 0.f, 0.f};
; #pragma unroll
;                 for (int dc = 0; dc < 4; ++dc) { const bf16x8 kf = *(const LAS bf16x8*)(Kl + (kb + q16) * MEM_KS + 32 * dc + 8 * kq);
;                     a = __builtin_amdgcn_mfma_f32_16x16x32_bf16(kf, qf[dc], a, 0, 0, 0); }
; #pragma unroll
;                 for (int e = 0; e < 4; ++e) mx = fmaxf(mx, a[e]);
;                 S[cc][tt] = a; }
	global_load_dwordx4 v[234:237], v[230:231], off
	global_load_dwordx4 v[242:245], v[230:231], off offset:64
	global_load_dwordx4 v[246:249], v[230:231], off offset:128
	global_load_dwordx4 v[250:253], v[230:231], off offset:192
	v_mul_f32_e32 v16, v16, v50
	v_mul_f32_e32 v17, v17, v50
	v_mul_f32_e32 v18, v18, v50
	v_mul_f32_e32 v19, v19, v50
	v_mul_f32_e32 v0, v0, v27
	v_mul_f32_e32 v1, v1, v26
	v_mul_f32_e32 v2, v2, v21
	v_mul_f32_e32 v3, v3, v20
	v_mul_f32_e32 v16, v16, v29
	v_mul_f32_e32 v17, v17, v28
	v_mul_f32_e32 v18, v18, v23
	v_mul_f32_e32 v19, v19, v22
	v_cvt_pk_bf16_f32 v0, v0, v1
	v_cvt_pk_bf16_f32 v1, v2, v3
	v_cvt_pk_bf16_f32 v2, v16, v17
	v_cvt_pk_bf16_f32 v3, v18, v19
	ds_read_b128 v[186:189], v91
	ds_read_b128 v[190:193], v91 offset:4352
	ds_read_b128 v[194:197], v91 offset:8704
	ds_read_b128 v[198:201], v91 offset:13056
	ds_read_b128 v[202:205], v91 offset:17408
	s_nop 0
	ds_read_b128 v[20:23], v91 offset:64
	s_nop 0
	ds_read_b128 v[28:31], v91 offset:4416
	s_nop 0
	ds_read_b128 v[36:39], v91 offset:8768
	s_nop 0
	ds_read_b128 v[44:47], v91 offset:13120
	s_nop 0
	ds_read_b128 v[52:55], v91 offset:17472
	ds_read_b128 v[56:59], v91 offset:21760
	ds_read_b128 v[60:63], v91 offset:21824
	ds_read_b128 v[64:67], v91 offset:26112
	ds_read_b128 v[68:71], v91 offset:26176
	ds_read_b128 v[72:75], v91 offset:30464
	ds_read_b128 v[76:79], v91 offset:30528
	ds_read_b128 v[102:105], v91 offset:34816
	ds_read_b128 v[106:109], v91 offset:34880
	ds_read_b128 v[110:113], v91 offset:39168
	ds_read_b128 v[114:117], v91 offset:39232
	ds_read_b128 v[118:121], v91 offset:43520
	ds_read_b128 v[122:125], v91 offset:43584
	ds_read_b128 v[126:129], v91 offset:47872
	ds_read_b128 v[130:133], v91 offset:47936
	ds_read_b128 v[134:137], v91 offset:52224
	ds_read_b128 v[138:141], v91 offset:52288
	ds_read_b128 v[142:145], v91 offset:56576
	ds_read_b128 v[146:149], v91 offset:56640
	ds_read_b128 v[150:153], v91 offset:60928
	ds_read_b128 v[154:157], v91 offset:60992
	ds_read_b128 v[158:161], v91 offset:65280
	ds_read_b128 v[162:165], v91 offset:65344
	s_waitcnt lgkmcnt(14)
	v_mfma_f32_16x16x32_bf16 v[16:19], v[186:189], v[8:11], 0
	v_mfma_f32_16x16x32_bf16 v[24:27], v[190:193], v[8:11], 0
	v_mfma_f32_16x16x32_bf16 v[32:35], v[194:197], v[8:11], 0
	v_mfma_f32_16x16x32_bf16 v[40:43], v[198:201], v[8:11], 0
	v_mfma_f32_16x16x32_bf16 v[48:51], v[202:205], v[8:11], 0
	v_mfma_f32_16x16x32_bf16 v[56:59], v[56:59], v[8:11], 0
	v_mfma_f32_16x16x32_bf16 v[64:67], v[64:67], v[8:11], 0
	v_mfma_f32_16x16x32_bf16 v[72:75], v[72:75], v[8:11], 0
	v_mfma_f32_16x16x32_bf16 v[102:105], v[102:105], v[8:11], 0
	s_waitcnt lgkmcnt(13)
	v_mfma_f32_16x16x32_bf16 v[110:113], v[110:113], v[8:11], 0
	s_waitcnt lgkmcnt(11)
	v_mfma_f32_16x16x32_bf16 v[118:121], v[118:121], v[8:11], 0
	s_waitcnt lgkmcnt(9)
	v_mfma_f32_16x16x32_bf16 v[126:129], v[126:129], v[8:11], 0
	s_waitcnt lgkmcnt(7)
	v_mfma_f32_16x16x32_bf16 v[134:137], v[134:137], v[8:11], 0
	s_waitcnt lgkmcnt(5)
	v_mfma_f32_16x16x32_bf16 v[142:145], v[142:145], v[8:11], 0
	s_waitcnt lgkmcnt(3)
	v_mfma_f32_16x16x32_bf16 v[150:153], v[150:153], v[8:11], 0
	s_waitcnt lgkmcnt(1)
	v_mfma_f32_16x16x32_bf16 v[8:11], v[158:161], v[8:11], 0
	v_mfma_f32_16x16x32_bf16 v[16:19], v[20:23], v[12:15], v[16:19]
	v_mfma_f32_16x16x32_bf16 v[20:23], v[28:31], v[12:15], v[24:27]
	v_mfma_f32_16x16x32_bf16 v[24:27], v[36:39], v[12:15], v[32:35]
	v_mfma_f32_16x16x32_bf16 v[28:31], v[44:47], v[12:15], v[40:43]
	v_mfma_f32_16x16x32_bf16 v[32:35], v[52:55], v[12:15], v[48:51]
	v_mfma_f32_16x16x32_bf16 v[36:39], v[60:63], v[12:15], v[56:59]
	v_mfma_f32_16x16x32_bf16 v[40:43], v[68:71], v[12:15], v[64:67]
	v_mfma_f32_16x16x32_bf16 v[44:47], v[76:79], v[12:15], v[72:75]
	v_mfma_f32_16x16x32_bf16 v[48:51], v[106:109], v[12:15], v[102:105]
	ds_read_b128 v[194:197], v91 offset:128
	ds_read_b128 v[198:201], v91 offset:4480
	ds_read_b128 v[202:205], v91 offset:8832
	v_mfma_f32_16x16x32_bf16 v[52:55], v[114:117], v[12:15], v[110:113]
	v_mfma_f32_16x16x32_bf16 v[56:59], v[122:125], v[12:15], v[118:121]
	v_mfma_f32_16x16x32_bf16 v[60:63], v[130:133], v[12:15], v[126:129]
	v_mfma_f32_16x16x32_bf16 v[64:67], v[138:141], v[12:15], v[134:137]
	v_mfma_f32_16x16x32_bf16 v[68:71], v[146:149], v[12:15], v[142:145]
	ds_read_b128 v[206:209], v91 offset:13184
	ds_read_b128 v[210:213], v91 offset:17536
	ds_read_b128 v[218:221], v91 offset:21888
	ds_read_b128 v[222:225], v91 offset:26240
	ds_read_b128 v[226:229], v91 offset:30592
	v_mfma_f32_16x16x32_bf16 v[102:105], v[154:157], v[12:15], v[150:153]
	s_waitcnt lgkmcnt(8)
	v_mfma_f32_16x16x32_bf16 v[8:11], v[162:165], v[12:15], v[8:11]
	s_nop 0
	ds_read_b128 v[106:109], v91 offset:192
	s_waitcnt lgkmcnt(8)
	v_mfma_f32_16x16x32_bf16 v[12:15], v[194:197], v[4:7], v[16:19]
	s_nop 2
	s_nop 0
	ds_read_b128 v[110:113], v91 offset:4544
	s_waitcnt lgkmcnt(8)
	v_mfma_f32_16x16x32_bf16 v[16:19], v[198:201], v[4:7], v[20:23]
	s_nop 2
	s_nop 0
	ds_read_b128 v[114:117], v91 offset:8896
	s_waitcnt lgkmcnt(8)
	v_mfma_f32_16x16x32_bf16 v[20:23], v[202:205], v[4:7], v[24:27]
	s_nop 2
	s_nop 0
	ds_read_b128 v[118:121], v91 offset:13248
	s_waitcnt lgkmcnt(8)
	ds_read_b128 v[186:189], v91 offset:34944
	ds_read_b128 v[190:193], v91 offset:39296
	ds_read_b128 v[194:197], v91 offset:43648
	ds_read_b128 v[198:201], v91 offset:48000
	ds_read_b128 v[202:205], v91 offset:52352
	v_mfma_f32_16x16x32_bf16 v[24:27], v[206:209], v[4:7], v[28:31]
	s_nop 2
	s_nop 0
	ds_read_b128 v[122:125], v91 offset:17600
	s_waitcnt lgkmcnt(13)
	v_mfma_f32_16x16x32_bf16 v[28:31], v[210:213], v[4:7], v[32:35]
	s_nop 2
	s_nop 0
	ds_read_b128 v[126:129], v91 offset:21952
	s_waitcnt lgkmcnt(13)
; #define LAS __attribute__((address_space(3)))
; __device__ __forceinline__ v2u vtr(const LAS bf16* p) { return __builtin_bit_cast(v2u, __builtin_amdgcn_ds_read_tr16_b64_v4i16((LAS v4i16_t*)p)); }
; template <bool SAMPLE>
; __device__ __forceinline__ void mem_unit(const Params& p, int l, LAS unsigned char* lds, int unit, int tid, int wave, int lane) {
;     ...
;         for (int cc = 0; cc < 8; ++cc)
; #pragma unroll
;             for (int tt = 0; tt < 2; ++tt) { const int kb = 32 * cc + 16 * tt; f32x4 a = (f32x4){0.f, 0.f, 0.f, 0.f};
; #pragma unroll
;                 for (int dc = 0; dc < 4; ++dc) { const bf16x8 kf = *(const LAS bf16x8*)(Kl + (kb + q16) * MEM_KS + 32 * dc + 8 * kq);
;                     a = __builtin_amdgcn_mfma_f32_16x16x32_bf16(kf, qf[dc], a, 0, 0, 0); }
; #pragma unroll
;                 for (int e = 0; e < 4; ++e) mx = fmaxf(mx, a[e]);
;                 S[cc][tt] = a; }
;         mx = fmaxf(mx, __shfl_xor(mx, 16)); mx = fmaxf(mx, __shfl_xor(mx, 32));
;     ...
; #pragma unroll
;         for (int dt = 0; dt < 8; ++dt) { f32x4 o = (f32x4){0.f, 0.f, 0.f, 0.f};
; #pragma unroll
;             for (int cc = 0; cc < 8; ++cc) { const LAS bf16* vp = Vt + (32 * cc + 4 * kq + (q16 >> 2)) * MEM_VS + 16 * dt + 4 * (q16 & 3);
;                 const v2u lo = vtr(vp), hi = vtr(vp + 16 * MEM_VS);
	v_mfma_f32_16x16x32_bf16 v[32:35], v[218:221], v[4:7], v[36:39]
	s_nop 2
	s_nop 0
	ds_read_b128 v[130:133], v91 offset:26304
	s_waitcnt lgkmcnt(13)
	v_mfma_f32_16x16x32_bf16 v[134:137], v[222:225], v[4:7], v[40:43]
	s_nop 0
	ds_read_b128 v[138:141], v91 offset:30656
	s_waitcnt lgkmcnt(13)
	v_mfma_f32_16x16x32_bf16 v[142:145], v[226:229], v[4:7], v[44:47]
	s_nop 0
	ds_read_b128 v[146:149], v91 offset:35008
	s_waitcnt lgkmcnt(9)
	ds_read_b128 v[206:209], v91 offset:56704
	ds_read_b128 v[210:213], v91 offset:61056
	ds_read_b128 v[218:221], v91 offset:65408
	v_mfma_f32_16x16x32_bf16 v[150:153], v[186:189], v[4:7], v[48:51]
	s_nop 0
	ds_read_b128 v[154:157], v91 offset:39360
	s_waitcnt lgkmcnt(12)
	v_mfma_f32_16x16x32_bf16 v[158:161], v[190:193], v[4:7], v[52:55]
	s_nop 0
	ds_read_b128 v[162:165], v91 offset:43712
	s_waitcnt lgkmcnt(12)
	v_mfma_f32_16x16x32_bf16 v[166:169], v[194:197], v[4:7], v[56:59]
	s_nop 0
	ds_read_b128 v[170:173], v91 offset:48064
	s_waitcnt lgkmcnt(12)
	v_mfma_f32_16x16x32_bf16 v[174:177], v[198:201], v[4:7], v[60:63]
	s_nop 0
	ds_read_b128 v[178:181], v91 offset:52416
	s_waitcnt lgkmcnt(12)
	v_mfma_f32_16x16x32_bf16 v[182:185], v[202:205], v[4:7], v[64:67]
	s_nop 0
	ds_read_b128 v[72:75], v91 offset:56768
	s_waitcnt lgkmcnt(7)
	v_mfma_f32_16x16x32_bf16 v[76:79], v[206:209], v[4:7], v[68:71]
	s_nop 0
	ds_read_b128 v[64:67], v91 offset:61120
	s_waitcnt lgkmcnt(7)
	v_mfma_f32_16x16x32_bf16 v[68:71], v[210:213], v[4:7], v[102:105]
	s_nop 0
	ds_read_b128 v[56:59], v91 offset:65472
	v_lshrrev_b32_e32 v91, 2, v90
	s_waitcnt lgkmcnt(7)
	v_mfma_f32_16x16x32_bf16 v[60:63], v[218:221], v[4:7], v[8:11]
	v_mfma_f32_16x16x32_bf16 v[52:55], v[106:109], v[0:3], v[12:15]
	v_mfma_f32_16x16x32_bf16 v[48:51], v[110:113], v[0:3], v[16:19]
	v_mfma_f32_16x16x32_bf16 v[44:47], v[114:117], v[0:3], v[20:23]
	v_mfma_f32_16x16x32_bf16 v[40:43], v[118:121], v[0:3], v[24:27]
	v_mfma_f32_16x16x32_bf16 v[36:39], v[122:125], v[0:3], v[28:31]
	v_mfma_f32_16x16x32_bf16 v[32:35], v[126:129], v[0:3], v[32:35]
	v_mfma_f32_16x16x32_bf16 v[28:31], v[130:133], v[0:3], v[134:137]
	v_mfma_f32_16x16x32_bf16 v[24:27], v[138:141], v[0:3], v[142:145]
	v_mfma_f32_16x16x32_bf16 v[20:23], v[146:149], v[0:3], v[150:153]
	v_mfma_f32_16x16x32_bf16 v[16:19], v[154:157], v[0:3], v[158:161]
	v_mfma_f32_16x16x32_bf16 v[12:15], v[162:165], v[0:3], v[166:169]
	v_mfma_f32_16x16x32_bf16 v[8:11], v[170:173], v[0:3], v[174:177]
	v_mfma_f32_16x16x32_bf16 v[4:7], v[178:181], v[0:3], v[182:185]
	v_mfma_f32_16x16x32_bf16 v[72:75], v[72:75], v[0:3], v[76:79]
	v_mfma_f32_16x16x32_bf16 v[66:69], v[64:67], v[0:3], v[68:71]
	s_nop 1
	v_lshlrev_b32_e32 v76, 3, v90
	v_add_u32_e32 v77, v91, v92
	v_and_b32_e32 v76, 24, v76
	s_waitcnt lgkmcnt(0)
	v_mfma_f32_16x16x32_bf16 v[0:3], v[56:59], v[0:3], v[60:63]
	v_max3_f32 v56, v52, s33, v53
	v_max3_f32 v56, v56, v54, v55
	v_max3_f32 v56, v56, v48, v49
	v_max3_f32 v56, v56, v50, v51
	v_max3_f32 v56, v56, v44, v45
	v_max3_f32 v56, v56, v46, v47
	v_max3_f32 v56, v56, v40, v41
	v_max3_f32 v56, v56, v42, v43
	v_max3_f32 v56, v56, v36, v37
	v_max3_f32 v56, v56, v38, v39
	v_max3_f32 v56, v56, v32, v33
	v_max3_f32 v56, v56, v34, v35
	v_max3_f32 v56, v56, v28, v29
	v_max3_f32 v56, v56, v30, v31
	v_max3_f32 v56, v56, v24, v25
	v_max3_f32 v56, v56, v26, v27
	v_max3_f32 v56, v56, v20, v21
	v_max3_f32 v56, v56, v22, v23
	v_max3_f32 v56, v56, v16, v17
	v_max3_f32 v56, v56, v18, v19
	v_max3_f32 v56, v56, v12, v13
	v_max3_f32 v56, v56, v14, v15
	v_max3_f32 v56, v56, v8, v9
	v_max3_f32 v56, v56, v10, v11
	v_max3_f32 v56, v56, v4, v5
	v_max3_f32 v56, v56, v6, v7
	v_max3_f32 v56, v56, v72, v73
	v_max3_f32 v56, v56, v74, v75
	v_max3_f32 v56, v56, v66, v67
	v_max3_f32 v56, v56, v68, v69
	v_max3_f32 v56, v56, v0, v1
	v_max3_f32 v56, v56, v2, v3
	ds_bpermute_b32 v57, v82, v56
	v_mul_lo_u32 v64, v77, s30
	v_add3_u32 v64, s90, v76, v64
	ds_read_b64_tr_b16 v[226:227], v64
	ds_read_b64_tr_b16 v[228:229], v64 offset:4352
	ds_read_b64_tr_b16 v[186:187], v64 offset:8704
	ds_read_b64_tr_b16 v[188:189], v64 offset:13056
	ds_read_b64_tr_b16 v[190:191], v64 offset:17408
	ds_read_b64_tr_b16 v[192:193], v64 offset:21760
	ds_read_b64_tr_b16 v[194:195], v64 offset:26112
	ds_read_b64_tr_b16 v[196:197], v64 offset:30464
	ds_read_b64_tr_b16 v[198:199], v64 offset:34816
	ds_read_b64_tr_b16 v[200:201], v64 offset:39168
	ds_read_b64_tr_b16 v[202:203], v64 offset:32
	ds_read_b64_tr_b16 v[204:205], v64 offset:4384
	s_waitcnt lgkmcnt(12)
	v_max_f32_e32 v57, v57, v57
	v_max_f32_e32 v56, v56, v57
	ds_bpermute_b32 v57, v100, v56
	s_waitcnt lgkmcnt(0)
; template <bool SAMPLE>
; __device__ __forceinline__ void mem_unit(const Params& p, int l, LAS unsigned char* lds, int unit, int tid, int wave, int lane) {
;     ...
;         float den = 0.f;
; #pragma unroll
;         for (int cc = 0; cc < 8; ++cc)
; #pragma unroll
;             for (int tt = 0; tt < 2; ++tt)
; #pragma unroll
;                 for (int e = 0; e < 4; ++e) { const float pe = __expf(S[cc][tt][e] - mx); S[cc][tt][e] = pe; den += pe; }
;         den += __shfl_xor(den, 16); den += __shfl_xor(den, 32);
;         const float rden = 1.f / den;
	v_max_f32_e32 v57, v57, v57
	v_max_f32_e32 v56, v56, v57
	v_sub_f32_e32 v52, v52, v56
	v_sub_f32_e32 v53, v53, v56
	v_mul_f32_e32 v52, 0x3fb8aa3b, v52
	v_sub_f32_e32 v54, v54, v56
	v_sub_f32_e32 v57, v72, v56
	v_sub_f32_e32 v58, v73, v56
	v_sub_f32_e32 v59, v74, v56
	v_sub_f32_e32 v60, v75, v56
	v_sub_f32_e32 v61, v66, v56
	v_sub_f32_e32 v62, v67, v56
	v_sub_f32_e32 v63, v68, v56
	v_sub_f32_e32 v65, v69, v56
	v_mul_f32_e32 v53, 0x3fb8aa3b, v53
	v_exp_f32_e32 v52, v52
	v_sub_f32_e32 v55, v55, v56
	v_sub_f32_e32 v48, v48, v56
	v_sub_f32_e32 v49, v49, v56
	v_sub_f32_e32 v50, v50, v56
	v_sub_f32_e32 v51, v51, v56
	v_sub_f32_e32 v44, v44, v56
	v_sub_f32_e32 v45, v45, v56
	v_sub_f32_e32 v46, v46, v56
	v_sub_f32_e32 v47, v47, v56
	v_sub_f32_e32 v40, v40, v56
	v_sub_f32_e32 v41, v41, v56
	v_sub_f32_e32 v42, v42, v56
	v_sub_f32_e32 v43, v43, v56
	v_sub_f32_e32 v36, v36, v56
	v_sub_f32_e32 v37, v37, v56
	v_sub_f32_e32 v38, v38, v56
	v_sub_f32_e32 v39, v39, v56
	v_sub_f32_e32 v32, v32, v56
	v_sub_f32_e32 v33, v33, v56
	v_sub_f32_e32 v34, v34, v56
	v_sub_f32_e32 v35, v35, v56
	v_sub_f32_e32 v28, v28, v56
	v_sub_f32_e32 v29, v29, v56
	v_sub_f32_e32 v30, v30, v56
	v_sub_f32_e32 v31, v31, v56
	v_sub_f32_e32 v24, v24, v56
	v_sub_f32_e32 v25, v25, v56
	v_sub_f32_e32 v26, v26, v56
	v_sub_f32_e32 v27, v27, v56
	v_sub_f32_e32 v20, v20, v56
	v_sub_f32_e32 v21, v21, v56
	v_sub_f32_e32 v22, v22, v56
	v_sub_f32_e32 v23, v23, v56
	v_sub_f32_e32 v16, v16, v56
	v_sub_f32_e32 v17, v17, v56
	v_sub_f32_e32 v18, v18, v56
	v_sub_f32_e32 v19, v19, v56
	v_sub_f32_e32 v12, v12, v56
	v_sub_f32_e32 v13, v13, v56
	v_sub_f32_e32 v14, v14, v56
	v_sub_f32_e32 v15, v15, v56
	v_sub_f32_e32 v8, v8, v56
	v_sub_f32_e32 v9, v9, v56
	v_sub_f32_e32 v10, v10, v56
	v_sub_f32_e32 v11, v11, v56
	v_sub_f32_e32 v4, v4, v56
	v_sub_f32_e32 v5, v5, v56
	v_sub_f32_e32 v6, v6, v56
	v_sub_f32_e32 v7, v7, v56
	v_sub_f32_e32 v0, v0, v56
	v_sub_f32_e32 v1, v1, v56
	v_sub_f32_e32 v2, v2, v56
	v_sub_f32_e32 v3, v3, v56
	v_mul_f32_e32 v54, 0x3fb8aa3b, v54
	v_mul_f32_e32 v56, 0x3fb8aa3b, v57
	v_mul_f32_e32 v57, 0x3fb8aa3b, v58
	v_mul_f32_e32 v58, 0x3fb8aa3b, v59
	v_mul_f32_e32 v59, 0x3fb8aa3b, v60
	v_mul_f32_e32 v60, 0x3fb8aa3b, v61
	v_mul_f32_e32 v61, 0x3fb8aa3b, v62
	v_mul_f32_e32 v62, 0x3fb8aa3b, v63
	v_mul_f32_e32 v63, 0x3fb8aa3b, v65
	v_exp_f32_e32 v65, v53
	v_mul_f32_e32 v55, 0x3fb8aa3b, v55
	v_exp_f32_e32 v66, v54
	v_mul_f32_e32 v48, 0x3fb8aa3b, v48
	v_exp_f32_e32 v67, v55
	v_mul_f32_e32 v49, 0x3fb8aa3b, v49
	v_mul_f32_e32 v0, 0x3fb8aa3b, v0
	v_exp_f32_e32 v68, v48
	v_add_f32_e32 v147, 0, v52
	v_mul_f32_e32 v50, 0x3fb8aa3b, v50
	v_exp_f32_e32 v69, v49
	v_exp_f32_e32 v143, v0
	v_cvt_pk_bf16_f32 v0, v52, v65
	v_add_f32_e32 v65, v65, v147
	v_mul_f32_e32 v51, 0x3fb8aa3b, v51
	v_exp_f32_e32 v70, v50
	v_add_f32_e32 v65, v66, v65
	v_mul_f32_e32 v44, 0x3fb8aa3b, v44
	v_exp_f32_e32 v71, v51
	v_add_f32_e32 v65, v67, v65
	v_mul_f32_e32 v45, 0x3fb8aa3b, v45
	v_exp_f32_e32 v72, v44
	v_add_f32_e32 v65, v68, v65
	v_mul_f32_e32 v46, 0x3fb8aa3b, v46
	v_exp_f32_e32 v73, v45
	v_add_f32_e32 v65, v69, v65
	v_mul_f32_e32 v47, 0x3fb8aa3b, v47
	v_exp_f32_e32 v74, v46
	v_add_f32_e32 v65, v70, v65
	v_mul_f32_e32 v40, 0x3fb8aa3b, v40
	v_exp_f32_e32 v75, v47
	v_add_f32_e32 v65, v71, v65
	v_mul_f32_e32 v41, 0x3fb8aa3b, v41
	v_mul_f32_e32 v42, 0x3fb8aa3b, v42
	v_mul_f32_e32 v43, 0x3fb8aa3b, v43
	v_mul_f32_e32 v36, 0x3fb8aa3b, v36
	v_mul_f32_e32 v37, 0x3fb8aa3b, v37
	v_mul_f32_e32 v38, 0x3fb8aa3b, v38
	v_mul_f32_e32 v39, 0x3fb8aa3b, v39
	v_mul_f32_e32 v32, 0x3fb8aa3b, v32
	v_mul_f32_e32 v33, 0x3fb8aa3b, v33
	v_mul_f32_e32 v34, 0x3fb8aa3b, v34
	v_mul_f32_e32 v35, 0x3fb8aa3b, v35
	v_mul_f32_e32 v28, 0x3fb8aa3b, v28
	v_mul_f32_e32 v29, 0x3fb8aa3b, v29
	v_mul_f32_e32 v30, 0x3fb8aa3b, v30
	v_mul_f32_e32 v31, 0x3fb8aa3b, v31
	v_mul_f32_e32 v24, 0x3fb8aa3b, v24
	v_mul_f32_e32 v25, 0x3fb8aa3b, v25
	v_mul_f32_e32 v26, 0x3fb8aa3b, v26
	v_mul_f32_e32 v27, 0x3fb8aa3b, v27
	v_mul_f32_e32 v20, 0x3fb8aa3b, v20
	v_mul_f32_e32 v21, 0x3fb8aa3b, v21
	v_mul_f32_e32 v22, 0x3fb8aa3b, v22
	v_mul_f32_e32 v23, 0x3fb8aa3b, v23
	v_mul_f32_e32 v16, 0x3fb8aa3b, v16
	v_mul_f32_e32 v17, 0x3fb8aa3b, v17
	v_mul_f32_e32 v18, 0x3fb8aa3b, v18
	v_mul_f32_e32 v19, 0x3fb8aa3b, v19
	v_mul_f32_e32 v12, 0x3fb8aa3b, v12
	v_mul_f32_e32 v13, 0x3fb8aa3b, v13
	v_mul_f32_e32 v14, 0x3fb8aa3b, v14
	v_mul_f32_e32 v15, 0x3fb8aa3b, v15
	v_mul_f32_e32 v8, 0x3fb8aa3b, v8
	v_mul_f32_e32 v9, 0x3fb8aa3b, v9
	v_mul_f32_e32 v10, 0x3fb8aa3b, v10
	v_mul_f32_e32 v11, 0x3fb8aa3b, v11
	v_mul_f32_e32 v4, 0x3fb8aa3b, v4
	v_mul_f32_e32 v5, 0x3fb8aa3b, v5
	v_mul_f32_e32 v6, 0x3fb8aa3b, v6
	v_mul_f32_e32 v7, 0x3fb8aa3b, v7
	v_mul_f32_e32 v1, 0x3fb8aa3b, v1
	v_mul_f32_e32 v2, 0x3fb8aa3b, v2
	v_mul_f32_e32 v3, 0x3fb8aa3b, v3
	v_exp_f32_e32 v76, v40
	v_add_f32_e32 v65, v72, v65
	v_exp_f32_e32 v77, v41
	v_exp_f32_e32 v78, v42
	v_exp_f32_e32 v79, v43
	v_exp_f32_e32 v90, v36
	v_exp_f32_e32 v91, v37
	v_exp_f32_e32 v101, v38
	v_exp_f32_e32 v102, v39
	v_exp_f32_e32 v103, v32
	v_exp_f32_e32 v104, v33
	v_exp_f32_e32 v105, v34
	v_exp_f32_e32 v106, v35
	v_exp_f32_e32 v107, v28
	v_exp_f32_e32 v108, v29
	v_exp_f32_e32 v109, v30
	v_exp_f32_e32 v110, v31
	v_exp_f32_e32 v111, v24
	v_exp_f32_e32 v112, v25
	v_exp_f32_e32 v113, v26
	v_exp_f32_e32 v114, v27
	v_exp_f32_e32 v115, v20
	v_exp_f32_e32 v116, v21
	v_exp_f32_e32 v117, v22
	v_exp_f32_e32 v118, v23
	v_exp_f32_e32 v119, v16
	v_exp_f32_e32 v120, v17
	v_exp_f32_e32 v121, v18
	v_exp_f32_e32 v122, v19
	v_exp_f32_e32 v123, v12
	v_exp_f32_e32 v124, v13
	v_exp_f32_e32 v125, v14
	v_exp_f32_e32 v126, v15
	v_exp_f32_e32 v127, v8
	v_exp_f32_e32 v128, v9
	v_exp_f32_e32 v129, v10
; #define LAS __attribute__((address_space(3)))
; __device__ __forceinline__ unsigned pk2(float lo, float hi) { return pg8::cvt_pk_bf16(lo, hi); }
; __device__ __forceinline__ bf16x8 pack8(const float (&o)[8]) { v4u w; w.x = pk2(o[0], o[1]); w.y = pk2(o[2], o[3]); w.z = pk2(o[4], o[5]); w.w = pk2(o[6], o[7]); return __builtin_bit_cast(bf16x8, w); }
; __device__ __forceinline__ v2u vtr(const LAS bf16* p) { return __builtin_bit_cast(v2u, __builtin_amdgcn_ds_read_tr16_b64_v4i16((LAS v4i16_t*)p)); }
; template <bool SAMPLE>
; __device__ __forceinline__ void mem_unit(const Params& p, int l, LAS unsigned char* lds, int unit, int tid, int wave, int lane) {
;     ...
;         for (int cc = 0; cc < 8; ++cc)
; #pragma unroll
;             for (int tt = 0; tt < 2; ++tt)
; #pragma unroll
;                 for (int e = 0; e < 4; ++e) { const float pe = __expf(S[cc][tt][e] - mx); S[cc][tt][e] = pe; den += pe; }
;         den += __shfl_xor(den, 16); den += __shfl_xor(den, 32);
;         const float rden = 1.f / den;
;         bf16x8 pf[8];
; #pragma unroll
;         for (int cc = 0; cc < 8; ++cc) { float t8[8];
; #pragma unroll
;             for (int e = 0; e < 4; ++e) { t8[e] = S[cc][0][e]; t8[4 + e] = S[cc][1][e]; }
;             pf[cc] = pack8(t8); }
; #pragma unroll
;         for (int dt = 0; dt < 8; ++dt) { f32x4 o = (f32x4){0.f, 0.f, 0.f, 0.f};
; #pragma unroll
;             for (int cc = 0; cc < 8; ++cc) { const LAS bf16* vp = Vt + (32 * cc + 4 * kq + (q16 >> 2)) * MEM_VS + 16 * dt + 4 * (q16 & 3);
;                 const v2u lo = vtr(vp), hi = vtr(vp + 16 * MEM_VS);
;                 v4u av; av.x = lo.x; av.y = lo.y; av.z = hi.x; av.w = hi.y;
;                 o = __builtin_amdgcn_mfma_f32_16x16x32_bf16(__builtin_bit_cast(bf16x8, av), pf[cc], o, 0, 0, 0); }
;             if (st) { v2u w; w.x = pk2(o[0] * rden, o[1] * rden); w.y = pk2(o[2] * rden, o[3] * rden);
;                 *(v2u*)(MO + row * 512 + h * 128 + 16 * dt + 4 * kq) = w; } }
	v_exp_f32_e32 v130, v11
	v_exp_f32_e32 v131, v4
	v_exp_f32_e32 v132, v5
	v_exp_f32_e32 v133, v6
	v_exp_f32_e32 v134, v7
	v_exp_f32_e32 v135, v56
	v_exp_f32_e32 v136, v57
	v_exp_f32_e32 v137, v58
	v_exp_f32_e32 v138, v59
	v_exp_f32_e32 v139, v60
	v_exp_f32_e32 v140, v61
	v_exp_f32_e32 v141, v62
	v_exp_f32_e32 v142, v63
	v_exp_f32_e32 v144, v1
	v_exp_f32_e32 v145, v2
	v_exp_f32_e32 v146, v3
	v_cvt_pk_bf16_f32 v1, v66, v67
	v_cvt_pk_bf16_f32 v2, v68, v69
	v_cvt_pk_bf16_f32 v3, v70, v71
	v_cvt_pk_bf16_f32 v4, v72, v73
	v_cvt_pk_bf16_f32 v5, v74, v75
	v_cvt_pk_bf16_f32 v6, v76, v77
	v_cvt_pk_bf16_f32 v7, v78, v79
	v_cvt_pk_bf16_f32 v8, v90, v91
	v_cvt_pk_bf16_f32 v9, v101, v102
	v_cvt_pk_bf16_f32 v10, v103, v104
	v_cvt_pk_bf16_f32 v11, v105, v106
	v_cvt_pk_bf16_f32 v12, v107, v108
	v_cvt_pk_bf16_f32 v13, v109, v110
	v_cvt_pk_bf16_f32 v14, v111, v112
	v_cvt_pk_bf16_f32 v15, v113, v114
	v_cvt_pk_bf16_f32 v16, v115, v116
	v_cvt_pk_bf16_f32 v17, v117, v118
	v_cvt_pk_bf16_f32 v18, v119, v120
	v_cvt_pk_bf16_f32 v19, v121, v122
	v_cvt_pk_bf16_f32 v24, v123, v124
	v_cvt_pk_bf16_f32 v25, v125, v126
	v_cvt_pk_bf16_f32 v26, v127, v128
	v_cvt_pk_bf16_f32 v27, v129, v130
	v_cvt_pk_bf16_f32 v28, v131, v132
	v_cvt_pk_bf16_f32 v29, v133, v134
	v_cvt_pk_bf16_f32 v30, v135, v136
	v_cvt_pk_bf16_f32 v31, v137, v138
	v_cvt_pk_bf16_f32 v20, v139, v140
	v_cvt_pk_bf16_f32 v21, v141, v142
	v_cvt_pk_bf16_f32 v22, v143, v144
	v_cvt_pk_bf16_f32 v23, v145, v146
	s_nop 7
	s_nop 1
	ds_read_b64_tr_b16 v[52:53], v64 offset:43520
	ds_read_b64_tr_b16 v[54:55], v64 offset:47872
	ds_read_b64_tr_b16 v[56:57], v64 offset:52224
	ds_read_b64_tr_b16 v[58:59], v64 offset:56576
	ds_read_b64_tr_b16 v[60:61], v64 offset:60928
	ds_read_b64_tr_b16 v[62:63], v64 offset:65280
	v_add_f32_e32 v65, v73, v65
	s_nop 0
	v_mfma_f32_16x16x32_bf16 v[32:35], v[226:229], v[0:3], 0
	v_add_f32_e32 v65, v74, v65
	v_add_f32_e32 v65, v75, v65
	v_add_f32_e32 v65, v76, v65
	v_add_f32_e32 v65, v77, v65
	s_nop 0
	ds_read_b64_tr_b16 v[206:207], v64 offset:8736
	ds_read_b64_tr_b16 v[208:209], v64 offset:13088
	ds_read_b64_tr_b16 v[210:211], v64 offset:17440
	ds_read_b64_tr_b16 v[212:213], v64 offset:21792
	ds_read_b64_tr_b16 v[218:219], v64 offset:26144
	ds_read_b64_tr_b16 v[220:221], v64 offset:30496
	ds_read_b64_tr_b16 v[222:223], v64 offset:34848
	ds_read_b64_tr_b16 v[224:225], v64 offset:39200
	ds_read_b64_tr_b16 v[226:227], v64 offset:43552
	ds_read_b64_tr_b16 v[228:229], v64 offset:47904
	v_mfma_f32_16x16x32_bf16 v[32:35], v[186:189], v[4:7], v[32:35]
	v_add_f32_e32 v36, v78, v65
	v_add_f32_e32 v36, v79, v36
	v_add_f32_e32 v36, v90, v36
	v_add_f32_e32 v36, v91, v36
	s_nop 0
	v_mfma_f32_16x16x32_bf16 v[32:35], v[190:193], v[8:11], v[32:35]
	v_add_f32_e32 v36, v101, v36
	v_add_f32_e32 v36, v102, v36
	v_add_f32_e32 v36, v103, v36
	v_add_f32_e32 v36, v104, v36
	s_nop 0
	v_mfma_f32_16x16x32_bf16 v[32:35], v[194:197], v[12:15], v[32:35]
	v_add_f32_e32 v36, v105, v36
	v_add_f32_e32 v36, v106, v36
	v_add_f32_e32 v36, v107, v36
	v_add_f32_e32 v36, v108, v36
	s_nop 0
	v_mfma_f32_16x16x32_bf16 v[32:35], v[198:201], v[16:19], v[32:35]
	v_add_f32_e32 v36, v109, v36
	v_add_f32_e32 v36, v110, v36
	v_add_f32_e32 v36, v111, v36
	v_add_f32_e32 v36, v112, v36
	s_waitcnt lgkmcnt(14)
	v_mfma_f32_16x16x32_bf16 v[32:35], v[52:55], v[24:27], v[32:35]
	v_add_f32_e32 v36, v113, v36
	v_add_f32_e32 v36, v114, v36
	v_add_f32_e32 v36, v115, v36
	v_add_f32_e32 v36, v116, v36
	s_waitcnt lgkmcnt(12)
	v_mfma_f32_16x16x32_bf16 v[32:35], v[56:59], v[28:31], v[32:35]
	v_add_f32_e32 v36, v117, v36
	v_add_f32_e32 v36, v118, v36
	v_add_f32_e32 v36, v119, v36
	v_add_f32_e32 v40, v120, v36
	s_waitcnt lgkmcnt(10)
	v_mfma_f32_16x16x32_bf16 v[36:39], v[60:63], v[20:23], v[32:35]
	s_nop 2
	v_add_f32_e32 v32, v121, v40
	v_add_f32_e32 v32, v122, v32
	v_add_f32_e32 v32, v123, v32
	v_add_f32_e32 v32, v124, v32
	v_add_f32_e32 v32, v125, v32
	v_add_f32_e32 v32, v126, v32
	v_add_f32_e32 v32, v127, v32
	v_add_f32_e32 v32, v128, v32
	v_add_f32_e32 v32, v129, v32
	v_add_f32_e32 v32, v130, v32
	v_add_f32_e32 v32, v131, v32
	v_add_f32_e32 v32, v132, v32
	v_add_f32_e32 v32, v133, v32
	v_add_f32_e32 v32, v134, v32
	v_add_f32_e32 v32, v135, v32
	v_add_f32_e32 v32, v136, v32
	v_add_f32_e32 v32, v137, v32
	v_add_f32_e32 v32, v138, v32
	v_add_f32_e32 v32, v139, v32
	v_add_f32_e32 v32, v140, v32
	v_add_f32_e32 v32, v141, v32
	v_add_f32_e32 v32, v142, v32
	v_add_f32_e32 v32, v143, v32
	v_add_f32_e32 v32, v144, v32
	v_add_f32_e32 v32, v145, v32
	v_add_f32_e32 v32, v146, v32
	ds_bpermute_b32 v33, v82, v32
	s_waitcnt lgkmcnt(0)
	v_add_f32_e32 v32, v32, v33
	ds_bpermute_b32 v33, v100, v32
	s_waitcnt lgkmcnt(0)
	v_add_f32_e32 v32, v32, v33
	v_div_scale_f32 v33, s[16:17], v32, v32, 1.0
	v_rcp_f32_e32 v35, v33
	v_div_scale_f32 v34, vcc, 1.0, v32, 1.0
	v_fma_f32 v40, -v33, v35, 1.0
	v_fmac_f32_e32 v35, v40, v35
	v_mul_f32_e32 v40, v34, v35
	v_fma_f32 v41, -v33, v40, v34
	v_fmac_f32_e32 v40, v41, v35
	v_fma_f32 v33, -v33, v40, v34
	v_div_fmas_f32 v33, v33, v35, v40
	v_div_fixup_f32 v34, v33, v32, 1.0
	v_mul_f32_e32 v32, v36, v34
	v_mul_f32_e32 v36, v39, v34
	v_mul_f32_e32 v33, v37, v34
	v_mul_f32_e32 v35, v38, v34
	v_cvt_pk_bf16_f32 v52, v32, v33
	v_cvt_pk_bf16_f32 v53, v35, v36
	s_nop 5
	v_mfma_f32_16x16x32_bf16 v[36:39], v[202:205], v[0:3], 0
	s_nop 1
	v_lshl_add_u64 v[32:33], s[2:3], 0, v[88:89]
	v_lshl_add_u64 v[32:33], v[92:93], 1, v[32:33]
	s_nop 0
	ds_read_b64_tr_b16 v[186:187], v64 offset:52256
	ds_read_b64_tr_b16 v[188:189], v64 offset:56608
	ds_read_b64_tr_b16 v[190:191], v64 offset:60960
	ds_read_b64_tr_b16 v[192:193], v64 offset:65312
	ds_read_b64_tr_b16 v[194:195], v64 offset:64
	ds_read_b64_tr_b16 v[196:197], v64 offset:4416
	ds_read_b64_tr_b16 v[198:199], v64 offset:8768
	ds_read_b64_tr_b16 v[200:201], v64 offset:13120
	ds_read_b64_tr_b16 v[202:203], v64 offset:17472
	ds_read_b64_tr_b16 v[204:205], v64 offset:21824
	v_mfma_f32_16x16x32_bf16 v[36:39], v[206:209], v[4:7], v[36:39]
	s_nop 2
	v_mfma_f32_16x16x32_bf16 v[36:39], v[210:213], v[8:11], v[36:39]
	s_nop 2
	v_mfma_f32_16x16x32_bf16 v[36:39], v[218:221], v[12:15], v[36:39]
	s_nop 2
	v_mfma_f32_16x16x32_bf16 v[36:39], v[222:225], v[16:19], v[36:39]
	s_nop 2
	global_store_dwordx2 v[32:33], v[52:53], off
	s_nop 0
	v_mfma_f32_16x16x32_bf16 v[36:39], v[226:229], v[24:27], v[36:39]
	s_waitcnt lgkmcnt(8)
; #define LAS __attribute__((address_space(3)))
; __device__ __forceinline__ unsigned pk2(float lo, float hi) { return pg8::cvt_pk_bf16(lo, hi); }
; __device__ __forceinline__ v2u vtr(const LAS bf16* p) { return __builtin_bit_cast(v2u, __builtin_amdgcn_ds_read_tr16_b64_v4i16((LAS v4i16_t*)p)); }
; template <bool SAMPLE>
; __device__ __forceinline__ void mem_unit(const Params& p, int l, LAS unsigned char* lds, int unit, int tid, int wave, int lane) {
;     ...
; #pragma unroll
;         for (int dt = 0; dt < 8; ++dt) { f32x4 o = (f32x4){0.f, 0.f, 0.f, 0.f};
; #pragma unroll
;             for (int cc = 0; cc < 8; ++cc) { const LAS bf16* vp = Vt + (32 * cc + 4 * kq + (q16 >> 2)) * MEM_VS + 16 * dt + 4 * (q16 & 3);
;                 const v2u lo = vtr(vp), hi = vtr(vp + 16 * MEM_VS);
;                 v4u av; av.x = lo.x; av.y = lo.y; av.z = hi.x; av.w = hi.y;
;                 o = __builtin_amdgcn_mfma_f32_16x16x32_bf16(__builtin_bit_cast(bf16x8, av), pf[cc], o, 0, 0, 0); }
;             if (st) { v2u w; w.x = pk2(o[0] * rden, o[1] * rden); w.y = pk2(o[2] * rden, o[3] * rden);
;                 *(v2u*)(MO + row * 512 + h * 128 + 16 * dt + 4 * kq) = w; } }
	ds_read_b64_tr_b16 v[206:207], v64 offset:26176
	ds_read_b64_tr_b16 v[208:209], v64 offset:30528
	ds_read_b64_tr_b16 v[210:211], v64 offset:34880
	ds_read_b64_tr_b16 v[212:213], v64 offset:39232
	ds_read_b64_tr_b16 v[218:219], v64 offset:43584
	ds_read_b64_tr_b16 v[220:221], v64 offset:47936
	ds_read_b64_tr_b16 v[222:223], v64 offset:52288
	ds_read_b64_tr_b16 v[224:225], v64 offset:56640
	ds_read_b64_tr_b16 v[226:227], v64 offset:60992
	ds_read_b64_tr_b16 v[228:229], v64 offset:65344
	v_mfma_f32_16x16x32_bf16 v[36:39], v[186:189], v[28:31], v[36:39]
	s_waitcnt lgkmcnt(15)
	v_mfma_f32_16x16x32_bf16 v[36:39], v[190:193], v[20:23], v[36:39]
	s_nop 7
	v_mul_f32_e32 v35, v34, v36
	v_mul_f32_e32 v36, v34, v37
	v_mul_f32_e32 v37, v34, v38
	v_mul_f32_e32 v38, v34, v39
	v_cvt_pk_bf16_f32 v52, v35, v36
	v_cvt_pk_bf16_f32 v53, v37, v38
	s_nop 4
	s_waitcnt lgkmcnt(14)
	v_mfma_f32_16x16x32_bf16 v[36:39], v[194:197], v[0:3], 0
	s_nop 1
	s_waitcnt lgkmcnt(12)
	v_mfma_f32_16x16x32_bf16 v[36:39], v[198:201], v[4:7], v[36:39]
	s_nop 1
	s_waitcnt lgkmcnt(10)
	v_mfma_f32_16x16x32_bf16 v[36:39], v[202:205], v[8:11], v[36:39]
	s_nop 1
	s_waitcnt lgkmcnt(8)
	ds_read_b64_tr_b16 v[186:187], v64 offset:96
	ds_read_b64_tr_b16 v[188:189], v64 offset:4448
	ds_read_b64_tr_b16 v[190:191], v64 offset:8800
	ds_read_b64_tr_b16 v[192:193], v64 offset:13152
	ds_read_b64_tr_b16 v[194:195], v64 offset:17504
	ds_read_b64_tr_b16 v[196:197], v64 offset:21856
	ds_read_b64_tr_b16 v[198:199], v64 offset:26208
	ds_read_b64_tr_b16 v[200:201], v64 offset:30560
	ds_read_b64_tr_b16 v[202:203], v64 offset:34912
	ds_read_b64_tr_b16 v[204:205], v64 offset:39264
	v_mfma_f32_16x16x32_bf16 v[36:39], v[206:209], v[12:15], v[36:39]
	s_nop 1
	s_waitcnt lgkmcnt(15)
	v_mfma_f32_16x16x32_bf16 v[36:39], v[210:213], v[16:19], v[36:39]
	s_nop 2
	global_store_dwordx2 v[32:33], v[52:53], off offset:32
	s_waitcnt lgkmcnt(14)
	v_mfma_f32_16x16x32_bf16 v[36:39], v[218:221], v[24:27], v[36:39]
	s_waitcnt lgkmcnt(12)
	v_mfma_f32_16x16x32_bf16 v[36:39], v[222:225], v[28:31], v[36:39]
	s_waitcnt lgkmcnt(10)
	v_mfma_f32_16x16x32_bf16 v[36:39], v[226:229], v[20:23], v[36:39]
	s_nop 7
	v_mul_f32_e32 v35, v34, v36
	v_mul_f32_e32 v36, v34, v37
	v_mul_f32_e32 v37, v34, v38
	v_mul_f32_e32 v38, v34, v39
	v_cvt_pk_bf16_f32 v52, v35, v36
	v_cvt_pk_bf16_f32 v53, v37, v38
	s_nop 4
	s_waitcnt lgkmcnt(8)
	ds_read_b64_tr_b16 v[206:207], v64 offset:43616
	ds_read_b64_tr_b16 v[208:209], v64 offset:47968
	ds_read_b64_tr_b16 v[210:211], v64 offset:52320
	ds_read_b64_tr_b16 v[212:213], v64 offset:56672
	ds_read_b64_tr_b16 v[218:219], v64 offset:61024
	ds_read_b64_tr_b16 v[220:221], v64 offset:65376
	ds_read_b64_tr_b16 v[222:223], v64 offset:128
	ds_read_b64_tr_b16 v[224:225], v64 offset:4480
	ds_read_b64_tr_b16 v[226:227], v64 offset:8832
	ds_read_b64_tr_b16 v[228:229], v64 offset:13184
	v_mfma_f32_16x16x32_bf16 v[36:39], v[186:189], v[0:3], 0
	s_nop 1
	s_waitcnt lgkmcnt(15)
	v_mfma_f32_16x16x32_bf16 v[36:39], v[190:193], v[4:7], v[36:39]
	s_nop 1
	s_waitcnt lgkmcnt(14)
	v_mfma_f32_16x16x32_bf16 v[36:39], v[194:197], v[8:11], v[36:39]
	s_nop 1
	s_waitcnt lgkmcnt(12)
	v_mfma_f32_16x16x32_bf16 v[36:39], v[198:201], v[12:15], v[36:39]
	s_nop 1
	s_waitcnt lgkmcnt(10)
	v_mfma_f32_16x16x32_bf16 v[36:39], v[202:205], v[16:19], v[36:39]
	s_nop 2
	global_store_dwordx2 v[32:33], v[52:53], off offset:64
	s_waitcnt lgkmcnt(8)
	ds_read_b64_tr_b16 v[186:187], v64 offset:17536
	ds_read_b64_tr_b16 v[188:189], v64 offset:21888
	ds_read_b64_tr_b16 v[190:191], v64 offset:26240
	ds_read_b64_tr_b16 v[192:193], v64 offset:30592
	ds_read_b64_tr_b16 v[194:195], v64 offset:34944
	ds_read_b64_tr_b16 v[196:197], v64 offset:39296
	ds_read_b64_tr_b16 v[198:199], v64 offset:43648
	ds_read_b64_tr_b16 v[200:201], v64 offset:48000
	ds_read_b64_tr_b16 v[202:203], v64 offset:52352
	ds_read_b64_tr_b16 v[204:205], v64 offset:56704
	v_mfma_f32_16x16x32_bf16 v[36:39], v[206:209], v[24:27], v[36:39]
	s_waitcnt lgkmcnt(15)
	v_mfma_f32_16x16x32_bf16 v[36:39], v[210:213], v[28:31], v[36:39]
	s_waitcnt lgkmcnt(14)
	v_mfma_f32_16x16x32_bf16 v[36:39], v[218:221], v[20:23], v[36:39]
	s_nop 7
	v_mul_f32_e32 v35, v34, v36
	v_mul_f32_e32 v36, v34, v37
	v_mul_f32_e32 v37, v34, v38
	v_mul_f32_e32 v38, v34, v39
	v_cvt_pk_bf16_f32 v52, v35, v36
	v_cvt_pk_bf16_f32 v53, v37, v38
	s_nop 4
	s_waitcnt lgkmcnt(12)
	v_mfma_f32_16x16x32_bf16 v[36:39], v[222:225], v[0:3], 0
	s_nop 1
	s_waitcnt lgkmcnt(10)
	v_mfma_f32_16x16x32_bf16 v[36:39], v[226:229], v[4:7], v[36:39]
	s_nop 1
	s_waitcnt lgkmcnt(8)
	ds_read_b64_tr_b16 v[206:207], v64 offset:61056
	ds_read_b64_tr_b16 v[208:209], v64 offset:65408
	ds_read_b64_tr_b16 v[210:211], v64 offset:160
	ds_read_b64_tr_b16 v[212:213], v64 offset:4512
	ds_read_b64_tr_b16 v[218:219], v64 offset:8864
	ds_read_b64_tr_b16 v[220:221], v64 offset:13216
	ds_read_b64_tr_b16 v[222:223], v64 offset:17568
	ds_read_b64_tr_b16 v[224:225], v64 offset:21920
	ds_read_b64_tr_b16 v[226:227], v64 offset:26272
	ds_read_b64_tr_b16 v[228:229], v64 offset:30624
	v_mfma_f32_16x16x32_bf16 v[36:39], v[186:189], v[8:11], v[36:39]
	s_nop 1
	s_waitcnt lgkmcnt(15)
	v_mfma_f32_16x16x32_bf16 v[36:39], v[190:193], v[12:15], v[36:39]
	s_nop 1
	s_waitcnt lgkmcnt(14)
	v_mfma_f32_16x16x32_bf16 v[36:39], v[194:197], v[16:19], v[36:39]
	s_nop 2
	global_store_dwordx2 v[32:33], v[52:53], off offset:96
	s_waitcnt lgkmcnt(12)
; #define LAS __attribute__((address_space(3)))
; __device__ __forceinline__ unsigned pk2(float lo, float hi) { return pg8::cvt_pk_bf16(lo, hi); }
; __device__ __forceinline__ v2u vtr(const LAS bf16* p) { return __builtin_bit_cast(v2u, __builtin_amdgcn_ds_read_tr16_b64_v4i16((LAS v4i16_t*)p)); }
; template <bool SAMPLE>
; __device__ __forceinline__ void mem_unit(const Params& p, int l, LAS unsigned char* lds, int unit, int tid, int wave, int lane) {
;     ...
; #pragma unroll
;         for (int dt = 0; dt < 8; ++dt) { f32x4 o = (f32x4){0.f, 0.f, 0.f, 0.f};
; #pragma unroll
;             for (int cc = 0; cc < 8; ++cc) { const LAS bf16* vp = Vt + (32 * cc + 4 * kq + (q16 >> 2)) * MEM_VS + 16 * dt + 4 * (q16 & 3);
;                 const v2u lo = vtr(vp), hi = vtr(vp + 16 * MEM_VS);
;                 v4u av; av.x = lo.x; av.y = lo.y; av.z = hi.x; av.w = hi.y;
;                 o = __builtin_amdgcn_mfma_f32_16x16x32_bf16(__builtin_bit_cast(bf16x8, av), pf[cc], o, 0, 0, 0); }
;             if (st) { v2u w; w.x = pk2(o[0] * rden, o[1] * rden); w.y = pk2(o[2] * rden, o[3] * rden);
;                 *(v2u*)(MO + row * 512 + h * 128 + 16 * dt + 4 * kq) = w; } }
	v_mfma_f32_16x16x32_bf16 v[36:39], v[198:201], v[24:27], v[36:39]
	s_waitcnt lgkmcnt(10)
	v_mfma_f32_16x16x32_bf16 v[36:39], v[202:205], v[28:31], v[36:39]
	s_waitcnt lgkmcnt(8)
	ds_read_b64_tr_b16 v[186:187], v64 offset:34976
	ds_read_b64_tr_b16 v[188:189], v64 offset:39328
	ds_read_b64_tr_b16 v[190:191], v64 offset:43680
	ds_read_b64_tr_b16 v[192:193], v64 offset:48032
	ds_read_b64_tr_b16 v[194:195], v64 offset:52384
	ds_read_b64_tr_b16 v[196:197], v64 offset:56736
	ds_read_b64_tr_b16 v[198:199], v64 offset:61088
	ds_read_b64_tr_b16 v[200:201], v64 offset:65440
	ds_read_b64_tr_b16 v[202:203], v64 offset:192
	ds_read_b64_tr_b16 v[204:205], v64 offset:4544
	v_mfma_f32_16x16x32_bf16 v[36:39], v[206:209], v[20:23], v[36:39]
	s_nop 7
	v_mul_f32_e32 v35, v34, v36
	v_mul_f32_e32 v36, v34, v37
	v_mul_f32_e32 v37, v34, v38
	v_mul_f32_e32 v38, v34, v39
	v_cvt_pk_bf16_f32 v52, v35, v36
	v_cvt_pk_bf16_f32 v53, v37, v38
	s_nop 4
	s_waitcnt lgkmcnt(15)
	v_mfma_f32_16x16x32_bf16 v[36:39], v[210:213], v[0:3], 0
	s_nop 1
	s_waitcnt lgkmcnt(14)
	v_mfma_f32_16x16x32_bf16 v[36:39], v[218:221], v[4:7], v[36:39]
	s_nop 1
	s_waitcnt lgkmcnt(12)
	v_mfma_f32_16x16x32_bf16 v[36:39], v[222:225], v[8:11], v[36:39]
	s_nop 1
	s_waitcnt lgkmcnt(10)
	v_mfma_f32_16x16x32_bf16 v[36:39], v[226:229], v[12:15], v[36:39]
	s_nop 1
	s_waitcnt lgkmcnt(8)
	ds_read_b64_tr_b16 v[206:207], v64 offset:8896
	ds_read_b64_tr_b16 v[208:209], v64 offset:13248
	ds_read_b64_tr_b16 v[210:211], v64 offset:17600
	ds_read_b64_tr_b16 v[212:213], v64 offset:21952
	ds_read_b64_tr_b16 v[218:219], v64 offset:26304
	ds_read_b64_tr_b16 v[220:221], v64 offset:30656
	ds_read_b64_tr_b16 v[222:223], v64 offset:35008
	ds_read_b64_tr_b16 v[224:225], v64 offset:39360
	ds_read_b64_tr_b16 v[226:227], v64 offset:43712
	ds_read_b64_tr_b16 v[228:229], v64 offset:48064
	v_mfma_f32_16x16x32_bf16 v[36:39], v[186:189], v[16:19], v[36:39]
	s_nop 2
	global_store_dwordx2 v[32:33], v[52:53], off offset:128
	s_waitcnt lgkmcnt(15)
	v_mfma_f32_16x16x32_bf16 v[36:39], v[190:193], v[24:27], v[36:39]
	s_waitcnt lgkmcnt(14)
	v_mfma_f32_16x16x32_bf16 v[36:39], v[194:197], v[28:31], v[36:39]
	s_waitcnt lgkmcnt(12)
	v_mfma_f32_16x16x32_bf16 v[36:39], v[198:201], v[20:23], v[36:39]
	s_nop 7
	v_mul_f32_e32 v35, v34, v36
	v_mul_f32_e32 v36, v34, v37
	v_mul_f32_e32 v37, v34, v38
	v_mul_f32_e32 v38, v34, v39
	v_cvt_pk_bf16_f32 v52, v35, v36
	v_cvt_pk_bf16_f32 v53, v37, v38
	s_nop 4
	s_waitcnt lgkmcnt(10)
	v_mfma_f32_16x16x32_bf16 v[36:39], v[202:205], v[0:3], 0
	s_nop 1
	s_waitcnt lgkmcnt(8)
	ds_read_b64_tr_b16 v[186:187], v64 offset:61120
	ds_read_b64_tr_b16 v[188:189], v64 offset:65472
	ds_read_b64_tr_b16 v[190:191], v64 offset:224
	ds_read_b64_tr_b16 v[192:193], v64 offset:4576
	ds_read_b64_tr_b16 v[194:195], v64 offset:35040
	ds_read_b64_tr_b16 v[196:197], v64 offset:39392
	v_mfma_f32_16x16x32_bf16 v[36:39], v[206:209], v[4:7], v[36:39]
	s_nop 1
	s_waitcnt lgkmcnt(12)
	v_mfma_f32_16x16x32_bf16 v[36:39], v[210:213], v[8:11], v[36:39]
	s_nop 1
	s_waitcnt lgkmcnt(10)
	v_mfma_f32_16x16x32_bf16 v[36:39], v[218:221], v[12:15], v[36:39]
	s_nop 0
	ds_read_b64_tr_b16 v[48:49], v64 offset:52416
	s_waitcnt lgkmcnt(9)
	v_mfma_f32_16x16x32_bf16 v[36:39], v[222:225], v[16:19], v[36:39]
	ds_read_b64_tr_b16 v[50:51], v64 offset:56768
	s_nop 1
	global_store_dwordx2 v[32:33], v[52:53], off offset:160
	s_waitcnt lgkmcnt(8)
	v_mfma_f32_16x16x32_bf16 v[36:39], v[226:229], v[24:27], v[36:39]
	s_waitcnt lgkmcnt(0)
	v_mfma_f32_16x16x32_bf16 v[36:39], v[48:51], v[28:31], v[36:39]
	s_nop 0
	v_mfma_f32_16x16x32_bf16 v[36:39], v[186:189], v[20:23], v[36:39]
	s_nop 7
	v_mul_f32_e32 v35, v34, v36
	v_mul_f32_e32 v36, v34, v37
	v_mul_f32_e32 v37, v34, v38
	v_mul_f32_e32 v38, v34, v39
	v_cvt_pk_bf16_f32 v48, v35, v36
	v_cvt_pk_bf16_f32 v49, v37, v38
	s_nop 1
	ds_read_b64_tr_b16 v[40:41], v64 offset:8928
	ds_read_b64_tr_b16 v[42:43], v64 offset:13280
	ds_read_b64_tr_b16 v[44:45], v64 offset:17632
	s_nop 0
	v_mfma_f32_16x16x32_bf16 v[0:3], v[190:193], v[0:3], 0
	ds_read_b64_tr_b16 v[46:47], v64 offset:21984
	ds_read_b64_tr_b16 v[36:37], v64 offset:26336
	s_waitcnt lgkmcnt(3)
	v_mfma_f32_16x16x32_bf16 v[0:3], v[40:43], v[4:7], v[0:3]
	ds_read_b64_tr_b16 v[38:39], v64 offset:30688
	s_nop 0
	s_waitcnt lgkmcnt(2)
	v_mfma_f32_16x16x32_bf16 v[0:3], v[44:47], v[8:11], v[0:3]
	s_nop 0
	ds_read_b64_tr_b16 v[8:9], v64 offset:43744
	s_waitcnt lgkmcnt(1)
	v_mfma_f32_16x16x32_bf16 v[0:3], v[36:39], v[12:15], v[0:3]
	ds_read_b64_tr_b16 v[10:11], v64 offset:48096
	ds_read_b64_tr_b16 v[12:13], v64 offset:52448
	s_nop 0
	v_mfma_f32_16x16x32_bf16 v[0:3], v[194:197], v[16:19], v[0:3]
	ds_read_b64_tr_b16 v[14:15], v64 offset:56800
	ds_read_b64_tr_b16 v[4:5], v64 offset:61152
	ds_read_b64_tr_b16 v[6:7], v64 offset:65504
	global_store_dwordx2 v[32:33], v[48:49], off offset:192
	s_waitcnt lgkmcnt(4)
	v_mfma_f32_16x16x32_bf16 v[0:3], v[8:11], v[24:27], v[0:3]
	s_waitcnt lgkmcnt(2)
	v_mfma_f32_16x16x32_bf16 v[0:3], v[12:15], v[28:31], v[0:3]
	s_waitcnt lgkmcnt(0)
	v_mfma_f32_16x16x32_bf16 v[0:3], v[4:7], v[20:23], v[0:3]
	s_nop 7
	v_mul_f32_e32 v0, v34, v0
	v_mul_f32_e32 v1, v34, v1
	v_mul_f32_e32 v2, v34, v2
	v_mul_f32_e32 v3, v34, v3
	v_cvt_pk_bf16_f32 v0, v0, v1
	v_cvt_pk_bf16_f32 v1, v2, v3
	global_store_dwordx2 v[32:33], v[0:1], off offset:224
	s_cbranch_scc1 .LBB0_631
	s_nop 0
	s_nop 0
	s_nop 0
	s_nop 0
	s_nop 0
	s_nop 0
	s_nop 0
	s_nop 0
	s_nop 0
	s_nop 0
	s_nop 0
	s_barrier
	s_branch .LBB0_596

; __device__ __forceinline__ void unpack8(const v4u w, float (&o)[8]) { o[0] = bflo(w.x); o[1] = bfhi(w.x); o[2] = bflo(w.y); o[3] = bfhi(w.y); o[4] = bflo(w.z); o[5] = bfhi(w.z); o[6] = bflo(w.w); o[7] = bfhi(w.w); }
; template <bool SAMPLE>
; __device__ __forceinline__ void mem_unit(const Params& p, int l, LAS unsigned char* lds, int unit, int tid, int wave, int lane) {
;     ...
;         int q16 = lane & 15, kq = lane >> 4; asm volatile("" : "+v"(q16), "+v"(kq));
;         size_t row; bool st;
;         if (!SAMPLE) { row = (size_t)b * 8192 + (qt * 4 + qq) * 128 + 16 * wave + q16; st = true; } else { row = (size_t)MP + 8 * b + (q16 & 7); st = q16 < 8; }
;         bf16x8 qf[4];
;         {
;             float qv[4][8]; float ss = 0.f;
; #pragma unroll
;             for (int dc = 0; dc < 4; ++dc) { unpack8(*(const v4u*)(MQ + row * 512 + h * 128 + 32 * dc + 8 * kq), qv[dc]);
; #pragma unroll
;                 for (int e = 0; e < 8; ++e) ss += qv[dc][e] * qv[dc][e]; }
;             ss += __shfl_xor(ss, 16); ss += __shfl_xor(ss, 32);
;             const float rs = rsqrtf(ss * (1.f / 128.f) + EPS) * 0.08838834764831845f;
; #pragma unroll
;             for (int dc = 0; dc < 4; ++dc) { float qg[8]; pg8::ld8f(p.in[I_MQG] + l * 128 + 32 * dc + 8 * kq, qg);
.LBB0_2762:
	v_mov_b32_e32 v92, v95
	v_mov_b32_e32 v90, v94
	s_add_u32 s16, s10, s8
	s_addc_u32 s17, s18, s9
	v_ashrrev_i32_e32 v91, 31, v90
	v_lshl_add_u64 v[0:1], s[16:17], 0, v[90:91]
	v_lshlrev_b32_e32 v8, 3, v92
	v_lshlrev_b64 v[88:89], 10, v[0:1]
	v_ashrrev_i32_e32 v9, 31, v8
	v_lshl_add_u64 v[10:11], s[0:1], 0, v[88:89]
	v_lshlrev_b32_e32 v2, 4, v92
	v_mul_lo_u32 v3, v90, s22
	v_lshl_add_u64 v[24:25], v[8:9], 2, s[46:47]
	v_lshl_add_u64 v[20:21], v[8:9], 1, v[10:11]
	v_add3_u32 v91, 0, v2, v3
	global_load_dwordx4 v[0:3], v[24:25], off offset:528
	global_load_dwordx4 v[4:7], v[24:25], off offset:512
	s_cmp_lg_u32 s8, 0
	s_cbranch_scc1 .Lqpf_have_1
	global_load_dwordx4 v[234:237], v[20:21], off
	global_load_dwordx4 v[242:245], v[20:21], off offset:64
	global_load_dwordx4 v[246:249], v[20:21], off offset:128
	global_load_dwordx4 v[250:253], v[20:21], off offset:192
	s_waitcnt vmcnt(0)
	s_branch .Lqpf_go_1

; __device__ __forceinline__ void unpack8(const v4u w, float (&o)[8]) { o[0] = bflo(w.x); o[1] = bfhi(w.x); o[2] = bflo(w.y); o[3] = bfhi(w.y); o[4] = bflo(w.z); o[5] = bfhi(w.z); o[6] = bflo(w.w); o[7] = bfhi(w.w); }
; __device__ __forceinline__ bf16x8 pack8(const float (&o)[8]) { v4u w; w.x = pk2(o[0], o[1]); w.y = pk2(o[2], o[3]); w.z = pk2(o[4], o[5]); w.w = pk2(o[6], o[7]); return __builtin_bit_cast(bf16x8, w); }
; template <bool SAMPLE>
; __device__ __forceinline__ void mem_unit(const Params& p, int l, LAS unsigned char* lds, int unit, int tid, int wave, int lane) {
;     ...
;         bf16x8 qf[4];
;         {
;             float qv[4][8]; float ss = 0.f;
; #pragma unroll
;             for (int dc = 0; dc < 4; ++dc) { unpack8(*(const v4u*)(MQ + row * 512 + h * 128 + 32 * dc + 8 * kq), qv[dc]);
; #pragma unroll
;                 for (int e = 0; e < 8; ++e) ss += qv[dc][e] * qv[dc][e]; }
;             ss += __shfl_xor(ss, 16); ss += __shfl_xor(ss, 32);
;             const float rs = rsqrtf(ss * (1.f / 128.f) + EPS) * 0.08838834764831845f;
; #pragma unroll
;             for (int dc = 0; dc < 4; ++dc) { float qg[8]; pg8::ld8f(p.in[I_MQG] + l * 128 + 32 * dc + 8 * kq, qg);
; #pragma unroll
;                 for (int e = 0; e < 8; ++e) qv[dc][e] *= rs * qg[e];
;                 qf[dc] = pack8(qv[dc]); }
.Lqpf_go_1:
	s_mov_b32 s100, 0x20000
	s_mov_b32 s101, 0
	v_lshl_add_u64 v[230:231], v[20:21], 0, s[100:101]
	v_mov_b32_e32 v8, v234
	v_mov_b32_e32 v9, v235
	v_mov_b32_e32 v10, v236
	v_mov_b32_e32 v11, v237
	v_mov_b32_e32 v12, v242
	v_mov_b32_e32 v13, v243
	v_mov_b32_e32 v14, v244
	v_mov_b32_e32 v15, v245
	v_mov_b32_e32 v16, v246
	v_mov_b32_e32 v17, v247
	v_mov_b32_e32 v18, v248
	v_mov_b32_e32 v19, v249
	v_mov_b32_e32 v20, v250
	v_mov_b32_e32 v21, v251
	v_mov_b32_e32 v22, v252
	v_mov_b32_e32 v23, v253
	v_lshlrev_b32_e32 v92, 2, v92
	v_ashrrev_i32_e32 v93, 31, v92
	s_add_u32 s8, s8, 0x80
	s_addc_u32 s9, s9, 0
	s_cmpk_lg_i32 s8, 0x200
	s_waitcnt vmcnt(0)
	v_and_b32_e32 v31, 0xffff0000, v8
	v_lshlrev_b32_e32 v30, 16, v8
	v_mul_f32_e32 v50, v31, v31
	v_lshlrev_b32_e32 v32, 16, v9
	v_fmac_f32_e32 v50, v30, v30
	v_and_b32_e32 v33, 0xffff0000, v9
	v_fmac_f32_e32 v50, v32, v32
	v_lshlrev_b32_e32 v34, 16, v10
	v_fmac_f32_e32 v50, v33, v33
	v_and_b32_e32 v35, 0xffff0000, v10
	v_fmac_f32_e32 v50, v34, v34
	v_lshlrev_b32_e32 v36, 16, v11
	v_fmac_f32_e32 v50, v35, v35
	v_and_b32_e32 v37, 0xffff0000, v11
	v_fmac_f32_e32 v50, v36, v36
	s_waitcnt vmcnt(2)
	v_lshlrev_b32_e32 v38, 16, v12
	v_fmac_f32_e32 v50, v37, v37
	v_and_b32_e32 v39, 0xffff0000, v12
	v_fmac_f32_e32 v50, v38, v38
	v_lshlrev_b32_e32 v40, 16, v13
	v_fmac_f32_e32 v50, v39, v39
	v_and_b32_e32 v41, 0xffff0000, v13
	v_fmac_f32_e32 v50, v40, v40
	v_lshlrev_b32_e32 v42, 16, v14
	v_fmac_f32_e32 v50, v41, v41
	v_and_b32_e32 v43, 0xffff0000, v14
	v_fmac_f32_e32 v50, v42, v42
	v_lshlrev_b32_e32 v44, 16, v15
	v_fmac_f32_e32 v50, v43, v43
	v_and_b32_e32 v45, 0xffff0000, v15
	v_fmac_f32_e32 v50, v44, v44
	s_waitcnt vmcnt(1)
	v_lshlrev_b32_e32 v46, 16, v16
	v_fmac_f32_e32 v50, v45, v45
	v_and_b32_e32 v16, 0xffff0000, v16
	v_fmac_f32_e32 v50, v46, v46
	v_lshlrev_b32_e32 v47, 16, v17
	v_fmac_f32_e32 v50, v16, v16
	v_and_b32_e32 v17, 0xffff0000, v17
	v_fmac_f32_e32 v50, v47, v47
	v_lshlrev_b32_e32 v48, 16, v18
	v_fmac_f32_e32 v50, v17, v17
	v_and_b32_e32 v18, 0xffff0000, v18
	v_fmac_f32_e32 v50, v48, v48
	v_lshlrev_b32_e32 v49, 16, v19
	v_fmac_f32_e32 v50, v18, v18
	v_and_b32_e32 v19, 0xffff0000, v19
	s_waitcnt vmcnt(0)
	v_and_b32_e32 v26, 0xffff0000, v20
	v_lshlrev_b32_e32 v27, 16, v20
	v_fmac_f32_e32 v50, v49, v49
	v_pk_mul_f32 v[8:9], v[26:27], v[26:27]
	v_fmac_f32_e32 v50, v19, v19
	v_and_b32_e32 v20, 0xffff0000, v21
	v_lshlrev_b32_e32 v21, 16, v21
	v_add_f32_e32 v9, v9, v50
	v_pk_mul_f32 v[10:11], v[20:21], v[20:21]
	v_add_f32_e32 v8, v8, v9
	v_and_b32_e32 v28, 0xffff0000, v22
	v_lshlrev_b32_e32 v29, 16, v22
	v_add_f32_e32 v8, v11, v8
	v_pk_mul_f32 v[12:13], v[28:29], v[28:29]
	v_add_f32_e32 v8, v10, v8
	v_and_b32_e32 v22, 0xffff0000, v23
	v_lshlrev_b32_e32 v23, 16, v23
	v_add_f32_e32 v8, v13, v8
	v_pk_mul_f32 v[14:15], v[22:23], v[22:23]
	v_add_f32_e32 v8, v12, v8
	v_add_f32_e32 v8, v15, v8
	v_add_f32_e32 v8, v14, v8
	ds_bpermute_b32 v9, v82, v8
	s_waitcnt lgkmcnt(0)
	v_add_f32_e32 v8, v8, v9
	ds_bpermute_b32 v9, v100, v8
	s_waitcnt lgkmcnt(0)
	v_add_f32_e32 v8, v8, v9
	v_fmamk_f32 v8, v8, 0x3c000000, v98
	v_mul_f32_e32 v9, 0x4b800000, v8
	v_cmp_gt_f32_e32 vcc, s23, v8
	s_nop 1
	v_cndmask_b32_e32 v8, v8, v9, vcc
	v_rsq_f32_e32 v8, v8
	s_nop 0
	v_mul_f32_e32 v9, 0x45800000, v8
	v_cndmask_b32_e32 v8, v8, v9, vcc
	v_mul_f32_e32 v50, 0x3db504f3, v8
	v_mul_f32_e32 v4, v4, v50
	v_mul_f32_e32 v5, v5, v50
	v_mul_f32_e32 v6, v6, v50
	v_mul_f32_e32 v7, v7, v50
	v_mul_f32_e32 v0, v0, v50
	v_mul_f32_e32 v1, v1, v50
	v_mul_f32_e32 v2, v2, v50
	v_mul_f32_e32 v3, v3, v50
	v_mul_f32_e32 v4, v4, v30
	v_mul_f32_e32 v5, v5, v31
	v_mul_f32_e32 v6, v6, v32
	v_mul_f32_e32 v7, v7, v33
	v_mul_f32_e32 v0, v0, v34
	v_mul_f32_e32 v1, v1, v35
	v_mul_f32_e32 v2, v2, v36
	v_mul_f32_e32 v3, v3, v37
	v_cvt_pk_bf16_f32 v8, v4, v5
	v_cvt_pk_bf16_f32 v9, v6, v7
	v_cvt_pk_bf16_f32 v10, v0, v1
	v_cvt_pk_bf16_f32 v11, v2, v3
	global_load_dwordx4 v[0:3], v[24:25], off offset:640
	global_load_dwordx4 v[4:7], v[24:25], off offset:656
	s_waitcnt vmcnt(1)
	v_mul_f32_e32 v0, v0, v50
	v_mul_f32_e32 v1, v1, v50
	v_mul_f32_e32 v2, v2, v50
	v_mul_f32_e32 v3, v3, v50
	s_waitcnt vmcnt(0)
	v_mul_f32_e32 v4, v4, v50
	v_mul_f32_e32 v5, v5, v50
	v_mul_f32_e32 v6, v6, v50
	v_mul_f32_e32 v7, v7, v50
	v_mul_f32_e32 v0, v0, v38
	v_mul_f32_e32 v1, v1, v39
	v_mul_f32_e32 v2, v2, v40
	v_mul_f32_e32 v3, v3, v41
	v_mul_f32_e32 v4, v4, v42
	v_mul_f32_e32 v5, v5, v43
	v_mul_f32_e32 v6, v6, v44
	v_mul_f32_e32 v7, v7, v45
	v_cvt_pk_bf16_f32 v12, v0, v1
	v_cvt_pk_bf16_f32 v13, v2, v3
	v_cvt_pk_bf16_f32 v14, v4, v5
	v_cvt_pk_bf16_f32 v15, v6, v7
	global_load_dwordx4 v[0:3], v[24:25], off offset:768
	global_load_dwordx4 v[4:7], v[24:25], off offset:784
	s_waitcnt vmcnt(1)
	v_mul_f32_e32 v0, v0, v50
	v_mul_f32_e32 v1, v1, v50
	v_mul_f32_e32 v2, v2, v50
	v_mul_f32_e32 v3, v3, v50
	s_waitcnt vmcnt(0)
	v_mul_f32_e32 v4, v4, v50
	v_mul_f32_e32 v5, v5, v50
	v_mul_f32_e32 v6, v6, v50
	v_mul_f32_e32 v7, v7, v50
	v_mul_f32_e32 v0, v0, v46
	v_mul_f32_e32 v1, v1, v16
	v_mul_f32_e32 v2, v2, v47
	v_mul_f32_e32 v3, v3, v17
	v_mul_f32_e32 v16, v4, v48
	v_mul_f32_e32 v17, v5, v18
	v_mul_f32_e32 v18, v6, v49
	v_mul_f32_e32 v7, v7, v19
	v_cvt_pk_bf16_f32 v4, v0, v1
	v_cvt_pk_bf16_f32 v5, v2, v3
	v_cvt_pk_bf16_f32 v6, v16, v17
	v_cvt_pk_bf16_f32 v7, v18, v7
	global_load_dwordx4 v[0:3], v[24:25], off offset:896
	global_load_dwordx4 v[16:19], v[24:25], off offset:912
	s_waitcnt vmcnt(1)
	v_mul_f32_e32 v0, v0, v50
	v_mul_f32_e32 v1, v1, v50
	v_mul_f32_e32 v2, v2, v50
	v_mul_f32_e32 v3, v3, v50
	s_waitcnt vmcnt(0)
; #define LAS __attribute__((address_space(3)))
; __device__ __forceinline__ bf16x8 pack8(const float (&o)[8]) { v4u w; w.x = pk2(o[0], o[1]); w.y = pk2(o[2], o[3]); w.z = pk2(o[4], o[5]); w.w = pk2(o[6], o[7]); return __builtin_bit_cast(bf16x8, w); }
; template <bool SAMPLE>
; __device__ __forceinline__ void mem_unit(const Params& p, int l, LAS unsigned char* lds, int unit, int tid, int wave, int lane) {
;     ...
;             for (int dc = 0; dc < 4; ++dc) { float qg[8]; pg8::ld8f(p.in[I_MQG] + l * 128 + 32 * dc + 8 * kq, qg);
; #pragma unroll
;                 for (int e = 0; e < 8; ++e) qv[dc][e] *= rs * qg[e];
;                 qf[dc] = pack8(qv[dc]); }
;         }
;         f32x4 S[8][2]; float mx = -INFINITY;
; #pragma unroll
;         for (int cc = 0; cc < 8; ++cc)
; #pragma unroll
;             for (int tt = 0; tt < 2; ++tt) { const int kb = 32 * cc + 16 * tt; f32x4 a = (f32x4){0.f, 0.f, 0.f, 0.f};
; #pragma unroll
;                 for (int dc = 0; dc < 4; ++dc) { const bf16x8 kf = *(const LAS bf16x8*)(Kl + (kb + q16) * MEM_KS + 32 * dc + 8 * kq);
;                     a = __builtin_amdgcn_mfma_f32_16x16x32_bf16(kf, qf[dc], a, 0, 0, 0); }
; #pragma unroll
;                 for (int e = 0; e < 4; ++e) mx = fmaxf(mx, a[e]);
;                 S[cc][tt] = a; }
	global_load_dwordx4 v[234:237], v[230:231], off
	global_load_dwordx4 v[242:245], v[230:231], off offset:64
	global_load_dwordx4 v[246:249], v[230:231], off offset:128
	global_load_dwordx4 v[250:253], v[230:231], off offset:192
	v_mul_f32_e32 v16, v16, v50
	v_mul_f32_e32 v17, v17, v50
	v_mul_f32_e32 v18, v18, v50
	v_mul_f32_e32 v19, v19, v50
	v_mul_f32_e32 v0, v0, v27
	v_mul_f32_e32 v1, v1, v26
	v_mul_f32_e32 v2, v2, v21
	v_mul_f32_e32 v3, v3, v20
	v_mul_f32_e32 v16, v16, v29
	v_mul_f32_e32 v17, v17, v28
	v_mul_f32_e32 v18, v18, v23
	v_mul_f32_e32 v19, v19, v22
	v_cvt_pk_bf16_f32 v0, v0, v1
	v_cvt_pk_bf16_f32 v1, v2, v3
	v_cvt_pk_bf16_f32 v2, v16, v17
	v_cvt_pk_bf16_f32 v3, v18, v19
	ds_read_b128 v[186:189], v91
	ds_read_b128 v[190:193], v91 offset:4352
	ds_read_b128 v[194:197], v91 offset:8704
	ds_read_b128 v[198:201], v91 offset:13056
	ds_read_b128 v[202:205], v91 offset:17408
	s_nop 0
	ds_read_b128 v[20:23], v91 offset:64
	s_nop 0
	ds_read_b128 v[28:31], v91 offset:4416
	s_nop 0
	ds_read_b128 v[36:39], v91 offset:8768
	s_nop 0
	ds_read_b128 v[44:47], v91 offset:13120
	s_nop 0
	ds_read_b128 v[52:55], v91 offset:17472
	ds_read_b128 v[56:59], v91 offset:21760
	ds_read_b128 v[60:63], v91 offset:21824
	ds_read_b128 v[64:67], v91 offset:26112
	ds_read_b128 v[68:71], v91 offset:26176
	ds_read_b128 v[72:75], v91 offset:30464
	ds_read_b128 v[76:79], v91 offset:30528
	ds_read_b128 v[102:105], v91 offset:34816
	ds_read_b128 v[106:109], v91 offset:34880
	ds_read_b128 v[110:113], v91 offset:39168
	ds_read_b128 v[114:117], v91 offset:39232
	ds_read_b128 v[118:121], v91 offset:43520
	ds_read_b128 v[122:125], v91 offset:43584
	ds_read_b128 v[126:129], v91 offset:47872
	ds_read_b128 v[130:133], v91 offset:47936
	ds_read_b128 v[134:137], v91 offset:52224
	ds_read_b128 v[138:141], v91 offset:52288
	ds_read_b128 v[142:145], v91 offset:56576
	ds_read_b128 v[146:149], v91 offset:56640
	ds_read_b128 v[150:153], v91 offset:60928
	ds_read_b128 v[154:157], v91 offset:60992
	ds_read_b128 v[158:161], v91 offset:65280
	ds_read_b128 v[162:165], v91 offset:65344
	s_waitcnt lgkmcnt(14)
	v_mfma_f32_16x16x32_bf16 v[16:19], v[186:189], v[8:11], 0
	v_mfma_f32_16x16x32_bf16 v[24:27], v[190:193], v[8:11], 0
	v_mfma_f32_16x16x32_bf16 v[32:35], v[194:197], v[8:11], 0
	v_mfma_f32_16x16x32_bf16 v[40:43], v[198:201], v[8:11], 0
	v_mfma_f32_16x16x32_bf16 v[48:51], v[202:205], v[8:11], 0
	v_mfma_f32_16x16x32_bf16 v[56:59], v[56:59], v[8:11], 0
	v_mfma_f32_16x16x32_bf16 v[64:67], v[64:67], v[8:11], 0
	v_mfma_f32_16x16x32_bf16 v[72:75], v[72:75], v[8:11], 0
	v_mfma_f32_16x16x32_bf16 v[102:105], v[102:105], v[8:11], 0
	s_waitcnt lgkmcnt(13)
	v_mfma_f32_16x16x32_bf16 v[110:113], v[110:113], v[8:11], 0
	s_waitcnt lgkmcnt(11)
	v_mfma_f32_16x16x32_bf16 v[118:121], v[118:121], v[8:11], 0
	s_waitcnt lgkmcnt(9)
	v_mfma_f32_16x16x32_bf16 v[126:129], v[126:129], v[8:11], 0
	s_waitcnt lgkmcnt(7)
	v_mfma_f32_16x16x32_bf16 v[134:137], v[134:137], v[8:11], 0
	s_waitcnt lgkmcnt(5)
	v_mfma_f32_16x16x32_bf16 v[142:145], v[142:145], v[8:11], 0
	s_waitcnt lgkmcnt(3)
	v_mfma_f32_16x16x32_bf16 v[150:153], v[150:153], v[8:11], 0
	s_waitcnt lgkmcnt(1)
	v_mfma_f32_16x16x32_bf16 v[8:11], v[158:161], v[8:11], 0
	v_mfma_f32_16x16x32_bf16 v[16:19], v[20:23], v[12:15], v[16:19]
	v_mfma_f32_16x16x32_bf16 v[20:23], v[28:31], v[12:15], v[24:27]
	v_mfma_f32_16x16x32_bf16 v[24:27], v[36:39], v[12:15], v[32:35]
	v_mfma_f32_16x16x32_bf16 v[28:31], v[44:47], v[12:15], v[40:43]
	v_mfma_f32_16x16x32_bf16 v[32:35], v[52:55], v[12:15], v[48:51]
	v_mfma_f32_16x16x32_bf16 v[36:39], v[60:63], v[12:15], v[56:59]
	v_mfma_f32_16x16x32_bf16 v[40:43], v[68:71], v[12:15], v[64:67]
	v_mfma_f32_16x16x32_bf16 v[44:47], v[76:79], v[12:15], v[72:75]
	v_mfma_f32_16x16x32_bf16 v[48:51], v[106:109], v[12:15], v[102:105]
	ds_read_b128 v[194:197], v91 offset:128
	ds_read_b128 v[198:201], v91 offset:4480
	ds_read_b128 v[202:205], v91 offset:8832
	v_mfma_f32_16x16x32_bf16 v[52:55], v[114:117], v[12:15], v[110:113]
	v_mfma_f32_16x16x32_bf16 v[56:59], v[122:125], v[12:15], v[118:121]
	v_mfma_f32_16x16x32_bf16 v[60:63], v[130:133], v[12:15], v[126:129]
	v_mfma_f32_16x16x32_bf16 v[64:67], v[138:141], v[12:15], v[134:137]
	v_mfma_f32_16x16x32_bf16 v[68:71], v[146:149], v[12:15], v[142:145]
	ds_read_b128 v[206:209], v91 offset:13184
	ds_read_b128 v[210:213], v91 offset:17536
	ds_read_b128 v[218:221], v91 offset:21888
	ds_read_b128 v[222:225], v91 offset:26240
	ds_read_b128 v[226:229], v91 offset:30592
	v_mfma_f32_16x16x32_bf16 v[102:105], v[154:157], v[12:15], v[150:153]
	s_waitcnt lgkmcnt(8)
	v_mfma_f32_16x16x32_bf16 v[8:11], v[162:165], v[12:15], v[8:11]
	s_nop 0
	ds_read_b128 v[106:109], v91 offset:192
	s_waitcnt lgkmcnt(8)
	v_mfma_f32_16x16x32_bf16 v[12:15], v[194:197], v[4:7], v[16:19]
	s_nop 2
	s_nop 0
	ds_read_b128 v[110:113], v91 offset:4544
	s_waitcnt lgkmcnt(8)
	v_mfma_f32_16x16x32_bf16 v[16:19], v[198:201], v[4:7], v[20:23]
	s_nop 2
	s_nop 0
	ds_read_b128 v[114:117], v91 offset:8896
	s_waitcnt lgkmcnt(8)
	v_mfma_f32_16x16x32_bf16 v[20:23], v[202:205], v[4:7], v[24:27]
	s_nop 2
	s_nop 0
	ds_read_b128 v[118:121], v91 offset:13248
	s_waitcnt lgkmcnt(8)
	ds_read_b128 v[186:189], v91 offset:34944
	ds_read_b128 v[190:193], v91 offset:39296
	ds_read_b128 v[194:197], v91 offset:43648
	ds_read_b128 v[198:201], v91 offset:48000
	ds_read_b128 v[202:205], v91 offset:52352
	v_mfma_f32_16x16x32_bf16 v[24:27], v[206:209], v[4:7], v[28:31]
	s_nop 2
	s_nop 0
	ds_read_b128 v[122:125], v91 offset:17600
	s_waitcnt lgkmcnt(13)
	v_mfma_f32_16x16x32_bf16 v[28:31], v[210:213], v[4:7], v[32:35]
	s_nop 2
	s_nop 0
	ds_read_b128 v[126:129], v91 offset:21952
	s_waitcnt lgkmcnt(13)
; #define LAS __attribute__((address_space(3)))
; template <bool SAMPLE>
; __device__ __forceinline__ void mem_unit(const Params& p, int l, LAS unsigned char* lds, int unit, int tid, int wave, int lane) {
;     ...
;         for (int cc = 0; cc < 8; ++cc)
; #pragma unroll
;             for (int tt = 0; tt < 2; ++tt) { const int kb = 32 * cc + 16 * tt; f32x4 a = (f32x4){0.f, 0.f, 0.f, 0.f};
; #pragma unroll
;                 for (int dc = 0; dc < 4; ++dc) { const bf16x8 kf = *(const LAS bf16x8*)(Kl + (kb + q16) * MEM_KS + 32 * dc + 8 * kq);
;                     a = __builtin_amdgcn_mfma_f32_16x16x32_bf16(kf, qf[dc], a, 0, 0, 0); }
; #pragma unroll
;                 for (int e = 0; e < 4; ++e) mx = fmaxf(mx, a[e]);
;                 S[cc][tt] = a; }
;         mx = fmaxf(mx, __shfl_xor(mx, 16)); mx = fmaxf(mx, __shfl_xor(mx, 32));
	v_mfma_f32_16x16x32_bf16 v[32:35], v[218:221], v[4:7], v[36:39]
	s_nop 2
	s_nop 0
	ds_read_b128 v[130:133], v91 offset:26304
	s_waitcnt lgkmcnt(13)
	v_mfma_f32_16x16x32_bf16 v[134:137], v[222:225], v[4:7], v[40:43]
	s_nop 0
	ds_read_b128 v[138:141], v91 offset:30656
	s_waitcnt lgkmcnt(13)
	v_mfma_f32_16x16x32_bf16 v[142:145], v[226:229], v[4:7], v[44:47]
	s_nop 0
	ds_read_b128 v[146:149], v91 offset:35008
	s_waitcnt lgkmcnt(9)
	ds_read_b128 v[206:209], v91 offset:56704
	ds_read_b128 v[210:213], v91 offset:61056
	ds_read_b128 v[218:221], v91 offset:65408
	v_mfma_f32_16x16x32_bf16 v[150:153], v[186:189], v[4:7], v[48:51]
	s_nop 0
	ds_read_b128 v[154:157], v91 offset:39360
	s_waitcnt lgkmcnt(12)
	v_mfma_f32_16x16x32_bf16 v[158:161], v[190:193], v[4:7], v[52:55]
	s_nop 0
	ds_read_b128 v[162:165], v91 offset:43712
	s_waitcnt lgkmcnt(12)
	v_mfma_f32_16x16x32_bf16 v[166:169], v[194:197], v[4:7], v[56:59]
	s_nop 0
	ds_read_b128 v[170:173], v91 offset:48064
	s_waitcnt lgkmcnt(12)
	v_mfma_f32_16x16x32_bf16 v[174:177], v[198:201], v[4:7], v[60:63]
	s_nop 0
	ds_read_b128 v[178:181], v91 offset:52416
	s_waitcnt lgkmcnt(12)
	v_mfma_f32_16x16x32_bf16 v[182:185], v[202:205], v[4:7], v[64:67]
	s_nop 0
	ds_read_b128 v[72:75], v91 offset:56768
	s_waitcnt lgkmcnt(7)
	v_mfma_f32_16x16x32_bf16 v[76:79], v[206:209], v[4:7], v[68:71]
	s_nop 0
	ds_read_b128 v[64:67], v91 offset:61120
	s_waitcnt lgkmcnt(7)
	v_mfma_f32_16x16x32_bf16 v[68:71], v[210:213], v[4:7], v[102:105]
	s_nop 0
	ds_read_b128 v[56:59], v91 offset:65472
	v_lshrrev_b32_e32 v91, 2, v90
	s_waitcnt lgkmcnt(7)
	v_mfma_f32_16x16x32_bf16 v[60:63], v[218:221], v[4:7], v[8:11]
	v_mfma_f32_16x16x32_bf16 v[52:55], v[106:109], v[0:3], v[12:15]
	v_mfma_f32_16x16x32_bf16 v[48:51], v[110:113], v[0:3], v[16:19]
	v_mfma_f32_16x16x32_bf16 v[44:47], v[114:117], v[0:3], v[20:23]
	v_mfma_f32_16x16x32_bf16 v[40:43], v[118:121], v[0:3], v[24:27]
	v_mfma_f32_16x16x32_bf16 v[36:39], v[122:125], v[0:3], v[28:31]
	v_mfma_f32_16x16x32_bf16 v[32:35], v[126:129], v[0:3], v[32:35]
	v_mfma_f32_16x16x32_bf16 v[28:31], v[130:133], v[0:3], v[134:137]
	v_mfma_f32_16x16x32_bf16 v[24:27], v[138:141], v[0:3], v[142:145]
	v_mfma_f32_16x16x32_bf16 v[20:23], v[146:149], v[0:3], v[150:153]
	v_mfma_f32_16x16x32_bf16 v[16:19], v[154:157], v[0:3], v[158:161]
	v_mfma_f32_16x16x32_bf16 v[12:15], v[162:165], v[0:3], v[166:169]
	v_mfma_f32_16x16x32_bf16 v[8:11], v[170:173], v[0:3], v[174:177]
	v_mfma_f32_16x16x32_bf16 v[4:7], v[178:181], v[0:3], v[182:185]
	v_mfma_f32_16x16x32_bf16 v[72:75], v[72:75], v[0:3], v[76:79]
	v_mfma_f32_16x16x32_bf16 v[66:69], v[64:67], v[0:3], v[68:71]
	s_nop 1
	v_lshlrev_b32_e32 v76, 3, v90
	v_add_u32_e32 v77, v91, v92
	v_and_b32_e32 v76, 24, v76
	s_waitcnt lgkmcnt(0)
	v_mfma_f32_16x16x32_bf16 v[0:3], v[56:59], v[0:3], v[60:63]
	v_max3_f32 v56, v52, s24, v53
	v_max3_f32 v56, v56, v54, v55
	v_max3_f32 v56, v56, v48, v49
	v_max3_f32 v56, v56, v50, v51
	v_max3_f32 v56, v56, v44, v45
	v_max3_f32 v56, v56, v46, v47
	v_max3_f32 v56, v56, v40, v41
	v_max3_f32 v56, v56, v42, v43
	v_max3_f32 v56, v56, v36, v37
	v_max3_f32 v56, v56, v38, v39
	v_max3_f32 v56, v56, v32, v33
	v_max3_f32 v56, v56, v34, v35
	v_max3_f32 v56, v56, v28, v29
	v_max3_f32 v56, v56, v30, v31
	v_max3_f32 v56, v56, v24, v25
	v_max3_f32 v56, v56, v26, v27
	v_max3_f32 v56, v56, v20, v21
	v_max3_f32 v56, v56, v22, v23
	v_max3_f32 v56, v56, v16, v17
	v_max3_f32 v56, v56, v18, v19
	v_max3_f32 v56, v56, v12, v13
	v_max3_f32 v56, v56, v14, v15
	v_max3_f32 v56, v56, v8, v9
	v_max3_f32 v56, v56, v10, v11
	v_max3_f32 v56, v56, v4, v5
	v_max3_f32 v56, v56, v6, v7
	v_max3_f32 v56, v56, v72, v73
	v_max3_f32 v56, v56, v74, v75
	v_max3_f32 v56, v56, v66, v67
	v_max3_f32 v56, v56, v68, v69
	v_max3_f32 v56, v56, v0, v1
	v_max3_f32 v56, v56, v2, v3
	ds_bpermute_b32 v57, v82, v56
	v_mul_lo_u32 v64, v77, s22
	v_add3_u32 v64, s90, v76, v64
	ds_read_b64_tr_b16 v[226:227], v64
	ds_read_b64_tr_b16 v[228:229], v64 offset:4352
	ds_read_b64_tr_b16 v[186:187], v64 offset:8704
	ds_read_b64_tr_b16 v[188:189], v64 offset:13056
	ds_read_b64_tr_b16 v[190:191], v64 offset:17408
	ds_read_b64_tr_b16 v[192:193], v64 offset:21760
	ds_read_b64_tr_b16 v[194:195], v64 offset:26112
	ds_read_b64_tr_b16 v[196:197], v64 offset:30464
	ds_read_b64_tr_b16 v[198:199], v64 offset:34816
	ds_read_b64_tr_b16 v[200:201], v64 offset:39168
	ds_read_b64_tr_b16 v[202:203], v64 offset:32
	ds_read_b64_tr_b16 v[204:205], v64 offset:4384
	s_waitcnt lgkmcnt(12)
	v_max_f32_e32 v57, v57, v57
	v_max_f32_e32 v56, v56, v57
	ds_bpermute_b32 v57, v100, v56
	s_waitcnt lgkmcnt(0)
; template <bool SAMPLE>
; __device__ __forceinline__ void mem_unit(const Params& p, int l, LAS unsigned char* lds, int unit, int tid, int wave, int lane) {
;     ...
;         float den = 0.f;
; #pragma unroll
;         for (int cc = 0; cc < 8; ++cc)
; #pragma unroll
;             for (int tt = 0; tt < 2; ++tt)
; #pragma unroll
;                 for (int e = 0; e < 4; ++e) { const float pe = __expf(S[cc][tt][e] - mx); S[cc][tt][e] = pe; den += pe; }
;         den += __shfl_xor(den, 16); den += __shfl_xor(den, 32);
;         const float rden = 1.f / den;
	v_max_f32_e32 v57, v57, v57
	v_max_f32_e32 v56, v56, v57
	v_sub_f32_e32 v52, v52, v56
	v_sub_f32_e32 v53, v53, v56
	v_mul_f32_e32 v52, 0x3fb8aa3b, v52
	v_sub_f32_e32 v54, v54, v56
	v_sub_f32_e32 v57, v72, v56
	v_sub_f32_e32 v58, v73, v56
	v_sub_f32_e32 v59, v74, v56
	v_sub_f32_e32 v60, v75, v56
	v_sub_f32_e32 v61, v66, v56
	v_sub_f32_e32 v62, v67, v56
	v_sub_f32_e32 v63, v68, v56
	v_sub_f32_e32 v65, v69, v56
	v_mul_f32_e32 v53, 0x3fb8aa3b, v53
	v_exp_f32_e32 v52, v52
	v_sub_f32_e32 v55, v55, v56
	v_sub_f32_e32 v48, v48, v56
	v_sub_f32_e32 v49, v49, v56
	v_sub_f32_e32 v50, v50, v56
	v_sub_f32_e32 v51, v51, v56
	v_sub_f32_e32 v44, v44, v56
	v_sub_f32_e32 v45, v45, v56
	v_sub_f32_e32 v46, v46, v56
	v_sub_f32_e32 v47, v47, v56
	v_sub_f32_e32 v40, v40, v56
	v_sub_f32_e32 v41, v41, v56
	v_sub_f32_e32 v42, v42, v56
	v_sub_f32_e32 v43, v43, v56
	v_sub_f32_e32 v36, v36, v56
	v_sub_f32_e32 v37, v37, v56
	v_sub_f32_e32 v38, v38, v56
	v_sub_f32_e32 v39, v39, v56
	v_sub_f32_e32 v32, v32, v56
	v_sub_f32_e32 v33, v33, v56
	v_sub_f32_e32 v34, v34, v56
	v_sub_f32_e32 v35, v35, v56
	v_sub_f32_e32 v28, v28, v56
	v_sub_f32_e32 v29, v29, v56
	v_sub_f32_e32 v30, v30, v56
	v_sub_f32_e32 v31, v31, v56
	v_sub_f32_e32 v24, v24, v56
	v_sub_f32_e32 v25, v25, v56
	v_sub_f32_e32 v26, v26, v56
	v_sub_f32_e32 v27, v27, v56
	v_sub_f32_e32 v20, v20, v56
	v_sub_f32_e32 v21, v21, v56
	v_sub_f32_e32 v22, v22, v56
	v_sub_f32_e32 v23, v23, v56
	v_sub_f32_e32 v16, v16, v56
	v_sub_f32_e32 v17, v17, v56
	v_sub_f32_e32 v18, v18, v56
	v_sub_f32_e32 v19, v19, v56
	v_sub_f32_e32 v12, v12, v56
	v_sub_f32_e32 v13, v13, v56
	v_sub_f32_e32 v14, v14, v56
	v_sub_f32_e32 v15, v15, v56
	v_sub_f32_e32 v8, v8, v56
	v_sub_f32_e32 v9, v9, v56
	v_sub_f32_e32 v10, v10, v56
	v_sub_f32_e32 v11, v11, v56
	v_sub_f32_e32 v4, v4, v56
	v_sub_f32_e32 v5, v5, v56
	v_sub_f32_e32 v6, v6, v56
	v_sub_f32_e32 v7, v7, v56
	v_sub_f32_e32 v0, v0, v56
	v_sub_f32_e32 v1, v1, v56
	v_sub_f32_e32 v2, v2, v56
	v_sub_f32_e32 v3, v3, v56
	v_mul_f32_e32 v54, 0x3fb8aa3b, v54
	v_mul_f32_e32 v56, 0x3fb8aa3b, v57
	v_mul_f32_e32 v57, 0x3fb8aa3b, v58
	v_mul_f32_e32 v58, 0x3fb8aa3b, v59
	v_mul_f32_e32 v59, 0x3fb8aa3b, v60
	v_mul_f32_e32 v60, 0x3fb8aa3b, v61
	v_mul_f32_e32 v61, 0x3fb8aa3b, v62
	v_mul_f32_e32 v62, 0x3fb8aa3b, v63
	v_mul_f32_e32 v63, 0x3fb8aa3b, v65
	v_exp_f32_e32 v65, v53
	v_mul_f32_e32 v55, 0x3fb8aa3b, v55
	v_exp_f32_e32 v66, v54
	v_mul_f32_e32 v48, 0x3fb8aa3b, v48
	v_exp_f32_e32 v67, v55
	v_mul_f32_e32 v49, 0x3fb8aa3b, v49
	v_mul_f32_e32 v0, 0x3fb8aa3b, v0
	v_exp_f32_e32 v68, v48
	v_add_f32_e32 v147, 0, v52
	v_mul_f32_e32 v50, 0x3fb8aa3b, v50
	v_exp_f32_e32 v69, v49
	v_exp_f32_e32 v143, v0
	v_cvt_pk_bf16_f32 v0, v52, v65
	v_add_f32_e32 v65, v65, v147
	v_mul_f32_e32 v51, 0x3fb8aa3b, v51
	v_exp_f32_e32 v70, v50
	v_add_f32_e32 v65, v66, v65
	v_mul_f32_e32 v44, 0x3fb8aa3b, v44
	v_exp_f32_e32 v71, v51
	v_add_f32_e32 v65, v67, v65
	v_mul_f32_e32 v45, 0x3fb8aa3b, v45
	v_exp_f32_e32 v72, v44
	v_add_f32_e32 v65, v68, v65
	v_mul_f32_e32 v46, 0x3fb8aa3b, v46
	v_exp_f32_e32 v73, v45
	v_add_f32_e32 v65, v69, v65
	v_mul_f32_e32 v47, 0x3fb8aa3b, v47
	v_exp_f32_e32 v74, v46
	v_add_f32_e32 v65, v70, v65
	v_mul_f32_e32 v40, 0x3fb8aa3b, v40
	v_exp_f32_e32 v75, v47
	v_add_f32_e32 v65, v71, v65
	v_mul_f32_e32 v41, 0x3fb8aa3b, v41
	v_mul_f32_e32 v42, 0x3fb8aa3b, v42
	v_mul_f32_e32 v43, 0x3fb8aa3b, v43
	v_mul_f32_e32 v36, 0x3fb8aa3b, v36
	v_mul_f32_e32 v37, 0x3fb8aa3b, v37
	v_mul_f32_e32 v38, 0x3fb8aa3b, v38
	v_mul_f32_e32 v39, 0x3fb8aa3b, v39
	v_mul_f32_e32 v32, 0x3fb8aa3b, v32
	v_mul_f32_e32 v33, 0x3fb8aa3b, v33
	v_mul_f32_e32 v34, 0x3fb8aa3b, v34
	v_mul_f32_e32 v35, 0x3fb8aa3b, v35
	v_mul_f32_e32 v28, 0x3fb8aa3b, v28
	v_mul_f32_e32 v29, 0x3fb8aa3b, v29
	v_mul_f32_e32 v30, 0x3fb8aa3b, v30
	v_mul_f32_e32 v31, 0x3fb8aa3b, v31
	v_mul_f32_e32 v24, 0x3fb8aa3b, v24
	v_mul_f32_e32 v25, 0x3fb8aa3b, v25
	v_mul_f32_e32 v26, 0x3fb8aa3b, v26
	v_mul_f32_e32 v27, 0x3fb8aa3b, v27
	v_mul_f32_e32 v20, 0x3fb8aa3b, v20
	v_mul_f32_e32 v21, 0x3fb8aa3b, v21
	v_mul_f32_e32 v22, 0x3fb8aa3b, v22
	v_mul_f32_e32 v23, 0x3fb8aa3b, v23
	v_mul_f32_e32 v16, 0x3fb8aa3b, v16
	v_mul_f32_e32 v17, 0x3fb8aa3b, v17
	v_mul_f32_e32 v18, 0x3fb8aa3b, v18
	v_mul_f32_e32 v19, 0x3fb8aa3b, v19
	v_mul_f32_e32 v12, 0x3fb8aa3b, v12
	v_mul_f32_e32 v13, 0x3fb8aa3b, v13
	v_mul_f32_e32 v14, 0x3fb8aa3b, v14
	v_mul_f32_e32 v15, 0x3fb8aa3b, v15
	v_mul_f32_e32 v8, 0x3fb8aa3b, v8
	v_mul_f32_e32 v9, 0x3fb8aa3b, v9
	v_mul_f32_e32 v10, 0x3fb8aa3b, v10
	v_mul_f32_e32 v11, 0x3fb8aa3b, v11
	v_mul_f32_e32 v4, 0x3fb8aa3b, v4
	v_mul_f32_e32 v5, 0x3fb8aa3b, v5
	v_mul_f32_e32 v6, 0x3fb8aa3b, v6
	v_mul_f32_e32 v7, 0x3fb8aa3b, v7
	v_mul_f32_e32 v1, 0x3fb8aa3b, v1
	v_mul_f32_e32 v2, 0x3fb8aa3b, v2
	v_mul_f32_e32 v3, 0x3fb8aa3b, v3
	v_exp_f32_e32 v76, v40
	v_add_f32_e32 v65, v72, v65
	v_exp_f32_e32 v77, v41
	v_exp_f32_e32 v78, v42
	v_exp_f32_e32 v79, v43
	v_exp_f32_e32 v90, v36
	v_exp_f32_e32 v91, v37
	v_exp_f32_e32 v101, v38
	v_exp_f32_e32 v102, v39
	v_exp_f32_e32 v103, v32
	v_exp_f32_e32 v104, v33
	v_exp_f32_e32 v105, v34
	v_exp_f32_e32 v106, v35
	v_exp_f32_e32 v107, v28
	v_exp_f32_e32 v108, v29
	v_exp_f32_e32 v109, v30
	v_exp_f32_e32 v110, v31
	v_exp_f32_e32 v111, v24
	v_exp_f32_e32 v112, v25
	v_exp_f32_e32 v113, v26
	v_exp_f32_e32 v114, v27
	v_exp_f32_e32 v115, v20
	v_exp_f32_e32 v116, v21
	v_exp_f32_e32 v117, v22
	v_exp_f32_e32 v118, v23
	v_exp_f32_e32 v119, v16
	v_exp_f32_e32 v120, v17
	v_exp_f32_e32 v121, v18
	v_exp_f32_e32 v122, v19
	v_exp_f32_e32 v123, v12
	v_exp_f32_e32 v124, v13
	v_exp_f32_e32 v125, v14
	v_exp_f32_e32 v126, v15
	v_exp_f32_e32 v127, v8
	v_exp_f32_e32 v128, v9
	v_exp_f32_e32 v129, v10
; #define LAS __attribute__((address_space(3)))
; __device__ __forceinline__ unsigned pk2(float lo, float hi) { return pg8::cvt_pk_bf16(lo, hi); }
; __device__ __forceinline__ bf16x8 pack8(const float (&o)[8]) { v4u w; w.x = pk2(o[0], o[1]); w.y = pk2(o[2], o[3]); w.z = pk2(o[4], o[5]); w.w = pk2(o[6], o[7]); return __builtin_bit_cast(bf16x8, w); }
; __device__ __forceinline__ v2u vtr(const LAS bf16* p) { return __builtin_bit_cast(v2u, __builtin_amdgcn_ds_read_tr16_b64_v4i16((LAS v4i16_t*)p)); }
; template <bool SAMPLE>
; __device__ __forceinline__ void mem_unit(const Params& p, int l, LAS unsigned char* lds, int unit, int tid, int wave, int lane) {
;     ...
;         for (int cc = 0; cc < 8; ++cc)
; #pragma unroll
;             for (int tt = 0; tt < 2; ++tt)
; #pragma unroll
;                 for (int e = 0; e < 4; ++e) { const float pe = __expf(S[cc][tt][e] - mx); S[cc][tt][e] = pe; den += pe; }
;         den += __shfl_xor(den, 16); den += __shfl_xor(den, 32);
;         const float rden = 1.f / den;
;         bf16x8 pf[8];
; #pragma unroll
;         for (int cc = 0; cc < 8; ++cc) { float t8[8];
; #pragma unroll
;             for (int e = 0; e < 4; ++e) { t8[e] = S[cc][0][e]; t8[4 + e] = S[cc][1][e]; }
;             pf[cc] = pack8(t8); }
; #pragma unroll
;         for (int dt = 0; dt < 8; ++dt) { f32x4 o = (f32x4){0.f, 0.f, 0.f, 0.f};
; #pragma unroll
;             for (int cc = 0; cc < 8; ++cc) { const LAS bf16* vp = Vt + (32 * cc + 4 * kq + (q16 >> 2)) * MEM_VS + 16 * dt + 4 * (q16 & 3);
;                 const v2u lo = vtr(vp), hi = vtr(vp + 16 * MEM_VS);
;                 v4u av; av.x = lo.x; av.y = lo.y; av.z = hi.x; av.w = hi.y;
;                 o = __builtin_amdgcn_mfma_f32_16x16x32_bf16(__builtin_bit_cast(bf16x8, av), pf[cc], o, 0, 0, 0); }
;             if (st) { v2u w; w.x = pk2(o[0] * rden, o[1] * rden); w.y = pk2(o[2] * rden, o[3] * rden);
;                 *(v2u*)(MO + row * 512 + h * 128 + 16 * dt + 4 * kq) = w; } }
	v_exp_f32_e32 v130, v11
	v_exp_f32_e32 v131, v4
	v_exp_f32_e32 v132, v5
	v_exp_f32_e32 v133, v6
	v_exp_f32_e32 v134, v7
	v_exp_f32_e32 v135, v56
	v_exp_f32_e32 v136, v57
	v_exp_f32_e32 v137, v58
	v_exp_f32_e32 v138, v59
	v_exp_f32_e32 v139, v60
	v_exp_f32_e32 v140, v61
	v_exp_f32_e32 v141, v62
	v_exp_f32_e32 v142, v63
	v_exp_f32_e32 v144, v1
	v_exp_f32_e32 v145, v2
	v_exp_f32_e32 v146, v3
	v_cvt_pk_bf16_f32 v1, v66, v67
	v_cvt_pk_bf16_f32 v2, v68, v69
	v_cvt_pk_bf16_f32 v3, v70, v71
	v_cvt_pk_bf16_f32 v4, v72, v73
	v_cvt_pk_bf16_f32 v5, v74, v75
	v_cvt_pk_bf16_f32 v6, v76, v77
	v_cvt_pk_bf16_f32 v7, v78, v79
	v_cvt_pk_bf16_f32 v8, v90, v91
	v_cvt_pk_bf16_f32 v9, v101, v102
	v_cvt_pk_bf16_f32 v10, v103, v104
	v_cvt_pk_bf16_f32 v11, v105, v106
	v_cvt_pk_bf16_f32 v12, v107, v108
	v_cvt_pk_bf16_f32 v13, v109, v110
	v_cvt_pk_bf16_f32 v14, v111, v112
	v_cvt_pk_bf16_f32 v15, v113, v114
	v_cvt_pk_bf16_f32 v16, v115, v116
	v_cvt_pk_bf16_f32 v17, v117, v118
	v_cvt_pk_bf16_f32 v18, v119, v120
	v_cvt_pk_bf16_f32 v19, v121, v122
	v_cvt_pk_bf16_f32 v24, v123, v124
	v_cvt_pk_bf16_f32 v25, v125, v126
	v_cvt_pk_bf16_f32 v26, v127, v128
	v_cvt_pk_bf16_f32 v27, v129, v130
	v_cvt_pk_bf16_f32 v28, v131, v132
	v_cvt_pk_bf16_f32 v29, v133, v134
	v_cvt_pk_bf16_f32 v30, v135, v136
	v_cvt_pk_bf16_f32 v31, v137, v138
	v_cvt_pk_bf16_f32 v20, v139, v140
	v_cvt_pk_bf16_f32 v21, v141, v142
	v_cvt_pk_bf16_f32 v22, v143, v144
	v_cvt_pk_bf16_f32 v23, v145, v146
	s_nop 7
	s_nop 1
	ds_read_b64_tr_b16 v[52:53], v64 offset:43520
	ds_read_b64_tr_b16 v[54:55], v64 offset:47872
	ds_read_b64_tr_b16 v[56:57], v64 offset:52224
	ds_read_b64_tr_b16 v[58:59], v64 offset:56576
	ds_read_b64_tr_b16 v[60:61], v64 offset:60928
	ds_read_b64_tr_b16 v[62:63], v64 offset:65280
	v_add_f32_e32 v65, v73, v65
	s_nop 0
	v_mfma_f32_16x16x32_bf16 v[32:35], v[226:229], v[0:3], 0
	v_add_f32_e32 v65, v74, v65
	v_add_f32_e32 v65, v75, v65
	v_add_f32_e32 v65, v76, v65
	v_add_f32_e32 v65, v77, v65
	s_nop 0
	ds_read_b64_tr_b16 v[206:207], v64 offset:8736
	ds_read_b64_tr_b16 v[208:209], v64 offset:13088
	ds_read_b64_tr_b16 v[210:211], v64 offset:17440
	ds_read_b64_tr_b16 v[212:213], v64 offset:21792
	ds_read_b64_tr_b16 v[218:219], v64 offset:26144
	ds_read_b64_tr_b16 v[220:221], v64 offset:30496
	ds_read_b64_tr_b16 v[222:223], v64 offset:34848
	ds_read_b64_tr_b16 v[224:225], v64 offset:39200
	ds_read_b64_tr_b16 v[226:227], v64 offset:43552
	ds_read_b64_tr_b16 v[228:229], v64 offset:47904
	v_mfma_f32_16x16x32_bf16 v[32:35], v[186:189], v[4:7], v[32:35]
	v_add_f32_e32 v36, v78, v65
	v_add_f32_e32 v36, v79, v36
	v_add_f32_e32 v36, v90, v36
	v_add_f32_e32 v36, v91, v36
	s_nop 0
	v_mfma_f32_16x16x32_bf16 v[32:35], v[190:193], v[8:11], v[32:35]
	v_add_f32_e32 v36, v101, v36
	v_add_f32_e32 v36, v102, v36
	v_add_f32_e32 v36, v103, v36
	v_add_f32_e32 v36, v104, v36
	s_nop 0
	v_mfma_f32_16x16x32_bf16 v[32:35], v[194:197], v[12:15], v[32:35]
	v_add_f32_e32 v36, v105, v36
	v_add_f32_e32 v36, v106, v36
	v_add_f32_e32 v36, v107, v36
	v_add_f32_e32 v36, v108, v36
	s_nop 0
	v_mfma_f32_16x16x32_bf16 v[32:35], v[198:201], v[16:19], v[32:35]
	v_add_f32_e32 v36, v109, v36
	v_add_f32_e32 v36, v110, v36
	v_add_f32_e32 v36, v111, v36
	v_add_f32_e32 v36, v112, v36
	s_waitcnt lgkmcnt(14)
	v_mfma_f32_16x16x32_bf16 v[32:35], v[52:55], v[24:27], v[32:35]
	v_add_f32_e32 v36, v113, v36
	v_add_f32_e32 v36, v114, v36
	v_add_f32_e32 v36, v115, v36
	v_add_f32_e32 v36, v116, v36
	s_waitcnt lgkmcnt(12)
	v_mfma_f32_16x16x32_bf16 v[32:35], v[56:59], v[28:31], v[32:35]
	v_add_f32_e32 v36, v117, v36
	v_add_f32_e32 v36, v118, v36
	v_add_f32_e32 v36, v119, v36
	v_add_f32_e32 v40, v120, v36
	s_waitcnt lgkmcnt(10)
	v_mfma_f32_16x16x32_bf16 v[36:39], v[60:63], v[20:23], v[32:35]
	s_nop 2
	v_add_f32_e32 v32, v121, v40
	v_add_f32_e32 v32, v122, v32
	v_add_f32_e32 v32, v123, v32
	v_add_f32_e32 v32, v124, v32
	v_add_f32_e32 v32, v125, v32
	v_add_f32_e32 v32, v126, v32
	v_add_f32_e32 v32, v127, v32
	v_add_f32_e32 v32, v128, v32
	v_add_f32_e32 v32, v129, v32
	v_add_f32_e32 v32, v130, v32
	v_add_f32_e32 v32, v131, v32
	v_add_f32_e32 v32, v132, v32
	v_add_f32_e32 v32, v133, v32
	v_add_f32_e32 v32, v134, v32
	v_add_f32_e32 v32, v135, v32
	v_add_f32_e32 v32, v136, v32
	v_add_f32_e32 v32, v137, v32
	v_add_f32_e32 v32, v138, v32
	v_add_f32_e32 v32, v139, v32
	v_add_f32_e32 v32, v140, v32
	v_add_f32_e32 v32, v141, v32
	v_add_f32_e32 v32, v142, v32
	v_add_f32_e32 v32, v143, v32
	v_add_f32_e32 v32, v144, v32
	v_add_f32_e32 v32, v145, v32
	v_add_f32_e32 v32, v146, v32
	ds_bpermute_b32 v33, v82, v32
	s_waitcnt lgkmcnt(0)
	v_add_f32_e32 v32, v32, v33
	ds_bpermute_b32 v33, v100, v32
	s_waitcnt lgkmcnt(0)
	v_add_f32_e32 v32, v32, v33
	v_div_scale_f32 v33, s[16:17], v32, v32, 1.0
	v_rcp_f32_e32 v35, v33
	v_div_scale_f32 v34, vcc, 1.0, v32, 1.0
	v_fma_f32 v40, -v33, v35, 1.0
	v_fmac_f32_e32 v35, v40, v35
	v_mul_f32_e32 v40, v34, v35
	v_fma_f32 v41, -v33, v40, v34
	v_fmac_f32_e32 v40, v41, v35
	v_fma_f32 v33, -v33, v40, v34
	v_div_fmas_f32 v33, v33, v35, v40
	v_div_fixup_f32 v34, v33, v32, 1.0
	v_mul_f32_e32 v32, v36, v34
	v_mul_f32_e32 v36, v39, v34
	v_mul_f32_e32 v33, v37, v34
	v_mul_f32_e32 v35, v38, v34
	v_cvt_pk_bf16_f32 v52, v32, v33
	v_cvt_pk_bf16_f32 v53, v35, v36
	s_nop 5
	v_mfma_f32_16x16x32_bf16 v[36:39], v[202:205], v[0:3], 0
	s_nop 1
	v_lshl_add_u64 v[32:33], s[2:3], 0, v[88:89]
	v_lshl_add_u64 v[32:33], v[92:93], 1, v[32:33]
	s_nop 0
	ds_read_b64_tr_b16 v[186:187], v64 offset:52256
	ds_read_b64_tr_b16 v[188:189], v64 offset:56608
	ds_read_b64_tr_b16 v[190:191], v64 offset:60960
	ds_read_b64_tr_b16 v[192:193], v64 offset:65312
	ds_read_b64_tr_b16 v[194:195], v64 offset:64
	ds_read_b64_tr_b16 v[196:197], v64 offset:4416
	ds_read_b64_tr_b16 v[198:199], v64 offset:8768
	ds_read_b64_tr_b16 v[200:201], v64 offset:13120
	ds_read_b64_tr_b16 v[202:203], v64 offset:17472
	ds_read_b64_tr_b16 v[204:205], v64 offset:21824
	v_mfma_f32_16x16x32_bf16 v[36:39], v[206:209], v[4:7], v[36:39]
	s_nop 2
	v_mfma_f32_16x16x32_bf16 v[36:39], v[210:213], v[8:11], v[36:39]
	s_nop 2
	v_mfma_f32_16x16x32_bf16 v[36:39], v[218:221], v[12:15], v[36:39]
	s_nop 2
	v_mfma_f32_16x16x32_bf16 v[36:39], v[222:225], v[16:19], v[36:39]
	s_nop 2
	global_store_dwordx2 v[32:33], v[52:53], off
	s_nop 0
	v_mfma_f32_16x16x32_bf16 v[36:39], v[226:229], v[24:27], v[36:39]
	s_waitcnt lgkmcnt(8)
; #define LAS __attribute__((address_space(3)))
; __device__ __forceinline__ unsigned pk2(float lo, float hi) { return pg8::cvt_pk_bf16(lo, hi); }
; __device__ __forceinline__ v2u vtr(const LAS bf16* p) { return __builtin_bit_cast(v2u, __builtin_amdgcn_ds_read_tr16_b64_v4i16((LAS v4i16_t*)p)); }
; template <bool SAMPLE>
; __device__ __forceinline__ void mem_unit(const Params& p, int l, LAS unsigned char* lds, int unit, int tid, int wave, int lane) {
;     ...
; #pragma unroll
;         for (int dt = 0; dt < 8; ++dt) { f32x4 o = (f32x4){0.f, 0.f, 0.f, 0.f};
; #pragma unroll
;             for (int cc = 0; cc < 8; ++cc) { const LAS bf16* vp = Vt + (32 * cc + 4 * kq + (q16 >> 2)) * MEM_VS + 16 * dt + 4 * (q16 & 3);
;                 const v2u lo = vtr(vp), hi = vtr(vp + 16 * MEM_VS);
;                 v4u av; av.x = lo.x; av.y = lo.y; av.z = hi.x; av.w = hi.y;
;                 o = __builtin_amdgcn_mfma_f32_16x16x32_bf16(__builtin_bit_cast(bf16x8, av), pf[cc], o, 0, 0, 0); }
;             if (st) { v2u w; w.x = pk2(o[0] * rden, o[1] * rden); w.y = pk2(o[2] * rden, o[3] * rden);
;                 *(v2u*)(MO + row * 512 + h * 128 + 16 * dt + 4 * kq) = w; } }
	ds_read_b64_tr_b16 v[206:207], v64 offset:26176
	ds_read_b64_tr_b16 v[208:209], v64 offset:30528
	ds_read_b64_tr_b16 v[210:211], v64 offset:34880
	ds_read_b64_tr_b16 v[212:213], v64 offset:39232
	ds_read_b64_tr_b16 v[218:219], v64 offset:43584
	ds_read_b64_tr_b16 v[220:221], v64 offset:47936
	ds_read_b64_tr_b16 v[222:223], v64 offset:52288
	ds_read_b64_tr_b16 v[224:225], v64 offset:56640
	ds_read_b64_tr_b16 v[226:227], v64 offset:60992
	ds_read_b64_tr_b16 v[228:229], v64 offset:65344
	v_mfma_f32_16x16x32_bf16 v[36:39], v[186:189], v[28:31], v[36:39]
	s_waitcnt lgkmcnt(15)
	v_mfma_f32_16x16x32_bf16 v[36:39], v[190:193], v[20:23], v[36:39]
	s_nop 7
	v_mul_f32_e32 v35, v34, v36
	v_mul_f32_e32 v36, v34, v37
	v_mul_f32_e32 v37, v34, v38
	v_mul_f32_e32 v38, v34, v39
	v_cvt_pk_bf16_f32 v52, v35, v36
	v_cvt_pk_bf16_f32 v53, v37, v38
	s_nop 4
	s_waitcnt lgkmcnt(14)
	v_mfma_f32_16x16x32_bf16 v[36:39], v[194:197], v[0:3], 0
	s_nop 1
	s_waitcnt lgkmcnt(12)
	v_mfma_f32_16x16x32_bf16 v[36:39], v[198:201], v[4:7], v[36:39]
	s_nop 1
	s_waitcnt lgkmcnt(10)
	v_mfma_f32_16x16x32_bf16 v[36:39], v[202:205], v[8:11], v[36:39]
	s_nop 1
	s_waitcnt lgkmcnt(8)
	ds_read_b64_tr_b16 v[186:187], v64 offset:96
	ds_read_b64_tr_b16 v[188:189], v64 offset:4448
	ds_read_b64_tr_b16 v[190:191], v64 offset:8800
	ds_read_b64_tr_b16 v[192:193], v64 offset:13152
	ds_read_b64_tr_b16 v[194:195], v64 offset:17504
	ds_read_b64_tr_b16 v[196:197], v64 offset:21856
	ds_read_b64_tr_b16 v[198:199], v64 offset:26208
	ds_read_b64_tr_b16 v[200:201], v64 offset:30560
	ds_read_b64_tr_b16 v[202:203], v64 offset:34912
	ds_read_b64_tr_b16 v[204:205], v64 offset:39264
	v_mfma_f32_16x16x32_bf16 v[36:39], v[206:209], v[12:15], v[36:39]
	s_nop 1
	s_waitcnt lgkmcnt(15)
	v_mfma_f32_16x16x32_bf16 v[36:39], v[210:213], v[16:19], v[36:39]
	s_nop 2
	global_store_dwordx2 v[32:33], v[52:53], off offset:32
	s_waitcnt lgkmcnt(14)
	v_mfma_f32_16x16x32_bf16 v[36:39], v[218:221], v[24:27], v[36:39]
	s_waitcnt lgkmcnt(12)
	v_mfma_f32_16x16x32_bf16 v[36:39], v[222:225], v[28:31], v[36:39]
	s_waitcnt lgkmcnt(10)
	v_mfma_f32_16x16x32_bf16 v[36:39], v[226:229], v[20:23], v[36:39]
	s_nop 7
	v_mul_f32_e32 v35, v34, v36
	v_mul_f32_e32 v36, v34, v37
	v_mul_f32_e32 v37, v34, v38
	v_mul_f32_e32 v38, v34, v39
	v_cvt_pk_bf16_f32 v52, v35, v36
	v_cvt_pk_bf16_f32 v53, v37, v38
	s_nop 4
	s_waitcnt lgkmcnt(8)
	ds_read_b64_tr_b16 v[206:207], v64 offset:43616
	ds_read_b64_tr_b16 v[208:209], v64 offset:47968
	ds_read_b64_tr_b16 v[210:211], v64 offset:52320
	ds_read_b64_tr_b16 v[212:213], v64 offset:56672
	ds_read_b64_tr_b16 v[218:219], v64 offset:61024
	ds_read_b64_tr_b16 v[220:221], v64 offset:65376
	ds_read_b64_tr_b16 v[222:223], v64 offset:128
	ds_read_b64_tr_b16 v[224:225], v64 offset:4480
	ds_read_b64_tr_b16 v[226:227], v64 offset:8832
	ds_read_b64_tr_b16 v[228:229], v64 offset:13184
	v_mfma_f32_16x16x32_bf16 v[36:39], v[186:189], v[0:3], 0
	s_nop 1
	s_waitcnt lgkmcnt(15)
	v_mfma_f32_16x16x32_bf16 v[36:39], v[190:193], v[4:7], v[36:39]
	s_nop 1
	s_waitcnt lgkmcnt(14)
	v_mfma_f32_16x16x32_bf16 v[36:39], v[194:197], v[8:11], v[36:39]
	s_nop 1
	s_waitcnt lgkmcnt(12)
	v_mfma_f32_16x16x32_bf16 v[36:39], v[198:201], v[12:15], v[36:39]
	s_nop 1
	s_waitcnt lgkmcnt(10)
	v_mfma_f32_16x16x32_bf16 v[36:39], v[202:205], v[16:19], v[36:39]
	s_nop 2
	global_store_dwordx2 v[32:33], v[52:53], off offset:64
	s_waitcnt lgkmcnt(8)
	ds_read_b64_tr_b16 v[186:187], v64 offset:17536
	ds_read_b64_tr_b16 v[188:189], v64 offset:21888
	ds_read_b64_tr_b16 v[190:191], v64 offset:26240
	ds_read_b64_tr_b16 v[192:193], v64 offset:30592
	ds_read_b64_tr_b16 v[194:195], v64 offset:34944
	ds_read_b64_tr_b16 v[196:197], v64 offset:39296
	ds_read_b64_tr_b16 v[198:199], v64 offset:43648
	ds_read_b64_tr_b16 v[200:201], v64 offset:48000
	ds_read_b64_tr_b16 v[202:203], v64 offset:52352
	ds_read_b64_tr_b16 v[204:205], v64 offset:56704
	v_mfma_f32_16x16x32_bf16 v[36:39], v[206:209], v[24:27], v[36:39]
	s_waitcnt lgkmcnt(15)
	v_mfma_f32_16x16x32_bf16 v[36:39], v[210:213], v[28:31], v[36:39]
	s_waitcnt lgkmcnt(14)
	v_mfma_f32_16x16x32_bf16 v[36:39], v[218:221], v[20:23], v[36:39]
	s_nop 7
	v_mul_f32_e32 v35, v34, v36
	v_mul_f32_e32 v36, v34, v37
	v_mul_f32_e32 v37, v34, v38
	v_mul_f32_e32 v38, v34, v39
	v_cvt_pk_bf16_f32 v52, v35, v36
	v_cvt_pk_bf16_f32 v53, v37, v38
	s_nop 4
	s_waitcnt lgkmcnt(12)
	v_mfma_f32_16x16x32_bf16 v[36:39], v[222:225], v[0:3], 0
	s_nop 1
	s_waitcnt lgkmcnt(10)
	v_mfma_f32_16x16x32_bf16 v[36:39], v[226:229], v[4:7], v[36:39]
	s_nop 1
	s_waitcnt lgkmcnt(8)
	ds_read_b64_tr_b16 v[206:207], v64 offset:61056
	ds_read_b64_tr_b16 v[208:209], v64 offset:65408
	ds_read_b64_tr_b16 v[210:211], v64 offset:160
	ds_read_b64_tr_b16 v[212:213], v64 offset:4512
	ds_read_b64_tr_b16 v[218:219], v64 offset:8864
	ds_read_b64_tr_b16 v[220:221], v64 offset:13216
	ds_read_b64_tr_b16 v[222:223], v64 offset:17568
	ds_read_b64_tr_b16 v[224:225], v64 offset:21920
	ds_read_b64_tr_b16 v[226:227], v64 offset:26272
	ds_read_b64_tr_b16 v[228:229], v64 offset:30624
	v_mfma_f32_16x16x32_bf16 v[36:39], v[186:189], v[8:11], v[36:39]
	s_nop 1
	s_waitcnt lgkmcnt(15)
	v_mfma_f32_16x16x32_bf16 v[36:39], v[190:193], v[12:15], v[36:39]
	s_nop 1
	s_waitcnt lgkmcnt(14)
	v_mfma_f32_16x16x32_bf16 v[36:39], v[194:197], v[16:19], v[36:39]
	s_nop 2
	global_store_dwordx2 v[32:33], v[52:53], off offset:96
	s_waitcnt lgkmcnt(12)
; #define LAS __attribute__((address_space(3)))
; __device__ __forceinline__ unsigned pk2(float lo, float hi) { return pg8::cvt_pk_bf16(lo, hi); }
; __device__ __forceinline__ v2u vtr(const LAS bf16* p) { return __builtin_bit_cast(v2u, __builtin_amdgcn_ds_read_tr16_b64_v4i16((LAS v4i16_t*)p)); }
; template <bool SAMPLE>
; __device__ __forceinline__ void mem_unit(const Params& p, int l, LAS unsigned char* lds, int unit, int tid, int wave, int lane) {
;     ...
; #pragma unroll
;         for (int dt = 0; dt < 8; ++dt) { f32x4 o = (f32x4){0.f, 0.f, 0.f, 0.f};
; #pragma unroll
;             for (int cc = 0; cc < 8; ++cc) { const LAS bf16* vp = Vt + (32 * cc + 4 * kq + (q16 >> 2)) * MEM_VS + 16 * dt + 4 * (q16 & 3);
;                 const v2u lo = vtr(vp), hi = vtr(vp + 16 * MEM_VS);
;                 v4u av; av.x = lo.x; av.y = lo.y; av.z = hi.x; av.w = hi.y;
;                 o = __builtin_amdgcn_mfma_f32_16x16x32_bf16(__builtin_bit_cast(bf16x8, av), pf[cc], o, 0, 0, 0); }
;             if (st) { v2u w; w.x = pk2(o[0] * rden, o[1] * rden); w.y = pk2(o[2] * rden, o[3] * rden);
;                 *(v2u*)(MO + row * 512 + h * 128 + 16 * dt + 4 * kq) = w; } }
	v_mfma_f32_16x16x32_bf16 v[36:39], v[198:201], v[24:27], v[36:39]
	s_waitcnt lgkmcnt(10)
	v_mfma_f32_16x16x32_bf16 v[36:39], v[202:205], v[28:31], v[36:39]
	s_waitcnt lgkmcnt(8)
	ds_read_b64_tr_b16 v[186:187], v64 offset:34976
	ds_read_b64_tr_b16 v[188:189], v64 offset:39328
	ds_read_b64_tr_b16 v[190:191], v64 offset:43680
	ds_read_b64_tr_b16 v[192:193], v64 offset:48032
	ds_read_b64_tr_b16 v[194:195], v64 offset:52384
	ds_read_b64_tr_b16 v[196:197], v64 offset:56736
	ds_read_b64_tr_b16 v[198:199], v64 offset:61088
	ds_read_b64_tr_b16 v[200:201], v64 offset:65440
	ds_read_b64_tr_b16 v[202:203], v64 offset:192
	ds_read_b64_tr_b16 v[204:205], v64 offset:4544
	v_mfma_f32_16x16x32_bf16 v[36:39], v[206:209], v[20:23], v[36:39]
	s_nop 7
	v_mul_f32_e32 v35, v34, v36
	v_mul_f32_e32 v36, v34, v37
	v_mul_f32_e32 v37, v34, v38
	v_mul_f32_e32 v38, v34, v39
	v_cvt_pk_bf16_f32 v52, v35, v36
	v_cvt_pk_bf16_f32 v53, v37, v38
	s_nop 4
	s_waitcnt lgkmcnt(15)
	v_mfma_f32_16x16x32_bf16 v[36:39], v[210:213], v[0:3], 0
	s_nop 1
	s_waitcnt lgkmcnt(14)
	v_mfma_f32_16x16x32_bf16 v[36:39], v[218:221], v[4:7], v[36:39]
	s_nop 1
	s_waitcnt lgkmcnt(12)
	v_mfma_f32_16x16x32_bf16 v[36:39], v[222:225], v[8:11], v[36:39]
	s_nop 1
	s_waitcnt lgkmcnt(10)
	v_mfma_f32_16x16x32_bf16 v[36:39], v[226:229], v[12:15], v[36:39]
	s_nop 1
	s_waitcnt lgkmcnt(8)
	ds_read_b64_tr_b16 v[206:207], v64 offset:8896
	ds_read_b64_tr_b16 v[208:209], v64 offset:13248
	ds_read_b64_tr_b16 v[210:211], v64 offset:17600
	ds_read_b64_tr_b16 v[212:213], v64 offset:21952
	ds_read_b64_tr_b16 v[218:219], v64 offset:26304
	ds_read_b64_tr_b16 v[220:221], v64 offset:30656
	ds_read_b64_tr_b16 v[222:223], v64 offset:35008
	ds_read_b64_tr_b16 v[224:225], v64 offset:39360
	ds_read_b64_tr_b16 v[226:227], v64 offset:43712
	ds_read_b64_tr_b16 v[228:229], v64 offset:48064
	v_mfma_f32_16x16x32_bf16 v[36:39], v[186:189], v[16:19], v[36:39]
	s_nop 2
	global_store_dwordx2 v[32:33], v[52:53], off offset:128
	s_waitcnt lgkmcnt(15)
	v_mfma_f32_16x16x32_bf16 v[36:39], v[190:193], v[24:27], v[36:39]
	s_waitcnt lgkmcnt(14)
	v_mfma_f32_16x16x32_bf16 v[36:39], v[194:197], v[28:31], v[36:39]
	s_waitcnt lgkmcnt(12)
	v_mfma_f32_16x16x32_bf16 v[36:39], v[198:201], v[20:23], v[36:39]
	s_nop 7
	v_mul_f32_e32 v35, v34, v36
	v_mul_f32_e32 v36, v34, v37
	v_mul_f32_e32 v37, v34, v38
	v_mul_f32_e32 v38, v34, v39
	v_cvt_pk_bf16_f32 v52, v35, v36
	v_cvt_pk_bf16_f32 v53, v37, v38
	s_nop 4
	s_waitcnt lgkmcnt(10)
	v_mfma_f32_16x16x32_bf16 v[36:39], v[202:205], v[0:3], 0
	s_nop 1
	s_waitcnt lgkmcnt(8)
	ds_read_b64_tr_b16 v[186:187], v64 offset:61120
	ds_read_b64_tr_b16 v[188:189], v64 offset:65472
	ds_read_b64_tr_b16 v[190:191], v64 offset:224
	ds_read_b64_tr_b16 v[192:193], v64 offset:4576
	ds_read_b64_tr_b16 v[194:195], v64 offset:35040
	ds_read_b64_tr_b16 v[196:197], v64 offset:39392
	v_mfma_f32_16x16x32_bf16 v[36:39], v[206:209], v[4:7], v[36:39]
	s_nop 1
	s_waitcnt lgkmcnt(12)
	v_mfma_f32_16x16x32_bf16 v[36:39], v[210:213], v[8:11], v[36:39]
	s_nop 1
	s_waitcnt lgkmcnt(10)
	v_mfma_f32_16x16x32_bf16 v[36:39], v[218:221], v[12:15], v[36:39]
	s_nop 0
	ds_read_b64_tr_b16 v[48:49], v64 offset:52416
	s_waitcnt lgkmcnt(9)
	v_mfma_f32_16x16x32_bf16 v[36:39], v[222:225], v[16:19], v[36:39]
	ds_read_b64_tr_b16 v[50:51], v64 offset:56768
	s_nop 1
	global_store_dwordx2 v[32:33], v[52:53], off offset:160
	s_waitcnt lgkmcnt(8)
	v_mfma_f32_16x16x32_bf16 v[36:39], v[226:229], v[24:27], v[36:39]
	s_waitcnt lgkmcnt(0)
	v_mfma_f32_16x16x32_bf16 v[36:39], v[48:51], v[28:31], v[36:39]
	s_nop 0
	v_mfma_f32_16x16x32_bf16 v[36:39], v[186:189], v[20:23], v[36:39]
	s_nop 7
	v_mul_f32_e32 v35, v34, v36
	v_mul_f32_e32 v36, v34, v37
	v_mul_f32_e32 v37, v34, v38
	v_mul_f32_e32 v38, v34, v39
	v_cvt_pk_bf16_f32 v48, v35, v36
	v_cvt_pk_bf16_f32 v49, v37, v38
	s_nop 1
	ds_read_b64_tr_b16 v[40:41], v64 offset:8928
	ds_read_b64_tr_b16 v[42:43], v64 offset:13280
	ds_read_b64_tr_b16 v[44:45], v64 offset:17632
	s_nop 0
	v_mfma_f32_16x16x32_bf16 v[0:3], v[190:193], v[0:3], 0
	ds_read_b64_tr_b16 v[46:47], v64 offset:21984
	ds_read_b64_tr_b16 v[36:37], v64 offset:26336
	s_waitcnt lgkmcnt(3)
	v_mfma_f32_16x16x32_bf16 v[0:3], v[40:43], v[4:7], v[0:3]
	ds_read_b64_tr_b16 v[38:39], v64 offset:30688
	s_nop 0
	s_waitcnt lgkmcnt(2)
	v_mfma_f32_16x16x32_bf16 v[0:3], v[44:47], v[8:11], v[0:3]
	s_nop 0
	ds_read_b64_tr_b16 v[8:9], v64 offset:43744
	s_waitcnt lgkmcnt(1)
	v_mfma_f32_16x16x32_bf16 v[0:3], v[36:39], v[12:15], v[0:3]
	ds_read_b64_tr_b16 v[10:11], v64 offset:48096
	ds_read_b64_tr_b16 v[12:13], v64 offset:52448
	s_nop 0
	v_mfma_f32_16x16x32_bf16 v[0:3], v[194:197], v[16:19], v[0:3]
	ds_read_b64_tr_b16 v[14:15], v64 offset:56800
	ds_read_b64_tr_b16 v[4:5], v64 offset:61152
	ds_read_b64_tr_b16 v[6:7], v64 offset:65504
	global_store_dwordx2 v[32:33], v[48:49], off offset:192
	s_waitcnt lgkmcnt(4)
	v_mfma_f32_16x16x32_bf16 v[0:3], v[8:11], v[24:27], v[0:3]
	s_waitcnt lgkmcnt(2)
	v_mfma_f32_16x16x32_bf16 v[0:3], v[12:15], v[28:31], v[0:3]
	s_waitcnt lgkmcnt(0)
	v_mfma_f32_16x16x32_bf16 v[0:3], v[4:7], v[20:23], v[0:3]
	s_nop 7
	v_mul_f32_e32 v0, v34, v0
	v_mul_f32_e32 v1, v34, v1
	v_mul_f32_e32 v2, v34, v2
	v_mul_f32_e32 v3, v34, v3
	v_cvt_pk_bf16_f32 v0, v0, v1
	v_cvt_pk_bf16_f32 v1, v2, v3
	global_store_dwordx2 v[32:33], v[0:1], off offset:224
	s_cbranch_scc1 .LBB0_2762
	s_nop 0
	s_nop 0
	s_nop 0
	s_nop 0
	s_nop 0
	s_nop 0
	s_nop 0
	s_nop 0
	s_nop 0
	s_nop 0
	s_nop 0
	s_barrier
	s_branch .LBB0_2727
